# write-through (sc0 sc1) on all 16-byte global stores: theory = cheaper L2 writeback in grid barrier
# speedup vs baseline: 1.0063x; 1.0063x over previous
.LBB0_22:
	s_mul_hi_i32 s6, s3, 0x2e8ba2e9
	s_lshr_b32 s7, s6, 31
	s_ashr_i32 s6, s6, 4
	s_add_i32 s7, s6, s7
	s_mul_i32 s6, s7, 0xffffffa8
	s_mul_i32 s8, s7, 0xffffea00
	s_add_i32 s31, s3, s6
	s_add_i32 s6, s5, s8
	s_cmp_gt_i32 s31, 43
	s_cselect_b32 s31, 0xfffff500, 43
	s_cselect_b32 s33, 0x80, 0
	s_lshl_b32 s8, s7, 6
	s_and_b32 s34, s6, 64
	v_add_u32_e32 v2, s8, v16
	s_mul_i32 s9, s7, 0x1600
	s_ashr_i32 s7, s6, 31
	s_or_b32 s33, s34, s33
	v_mad_i64_i32 v[2:3], s[34:35], v2, s11, v[10:11]
	v_lshl_add_u64 v[2:3], s[6:7], 2, v[2:3]
	v_lshl_add_u64 v[14:15], v[2:3], 0, v[6:7]
	v_add_co_u32_e32 v100, vcc, s12, v14
	global_load_dwordx4 v[2:5], v[14:15], off nt
	s_nop 0
	v_addc_co_u32_e32 v101, vcc, 0, v15, vcc
	v_add_co_u32_e32 v102, vcc, s13, v14
	s_sub_i32 s31, s31, s9
	s_nop 0
	v_addc_co_u32_e32 v103, vcc, 0, v15, vcc
	v_add_co_u32_e32 v104, vcc, s14, v14
	s_ashr_i32 s9, s8, 31
	s_nop 0
	v_addc_co_u32_e32 v105, vcc, 0, v15, vcc
	v_add_co_u32_e32 v106, vcc, s15, v14
	s_add_i32 s31, s5, s31
	s_nop 0
	v_addc_co_u32_e32 v107, vcc, 0, v15, vcc
	v_add_co_u32_e32 v108, vcc, s20, v14
	v_lshl_add_u64 v[12:13], s[8:9], 1, v[8:9]
	s_nop 0
	v_addc_co_u32_e32 v109, vcc, 0, v15, vcc
	v_add_co_u32_e32 v110, vcc, s21, v14
	s_lshl_b32 s8, s31, 1
	s_nop 0
	v_addc_co_u32_e32 v111, vcc, 0, v15, vcc
	v_add_co_u32_e32 v112, vcc, s22, v14
	s_and_b32 s6, s8, 0xffffff00
	s_nop 0
	v_addc_co_u32_e32 v113, vcc, 0, v15, vcc
	v_add_co_u32_e32 v114, vcc, s23, v14
	s_or_b32 s6, s33, s6
	s_nop 0
	v_addc_co_u32_e32 v115, vcc, 0, v15, vcc
	v_add_co_u32_e32 v116, vcc, s24, v14
	s_add_i32 s3, s3, s38
	s_nop 0
	v_addc_co_u32_e32 v117, vcc, 0, v15, vcc
	v_add_co_u32_e32 v118, vcc, s25, v14
	s_add_i32 s5, s5, s10
	s_nop 0
	v_addc_co_u32_e32 v119, vcc, 0, v15, vcc
	v_add_co_u32_e32 v120, vcc, s26, v14
	s_cmpk_gt_i32 s3, 0x57f
	s_nop 0
	v_addc_co_u32_e32 v121, vcc, 0, v15, vcc
	v_add_co_u32_e32 v122, vcc, s27, v14
	s_nop 1
	v_addc_co_u32_e32 v123, vcc, 0, v15, vcc
	v_add_co_u32_e32 v124, vcc, s28, v14
	s_nop 1
	v_addc_co_u32_e32 v125, vcc, 0, v15, vcc
	v_add_co_u32_e32 v126, vcc, s29, v14
	s_nop 1
	v_addc_co_u32_e32 v127, vcc, 0, v15, vcc
	v_add_co_u32_e32 v14, vcc, s30, v14
	s_nop 1
	v_addc_co_u32_e32 v15, vcc, 0, v15, vcc
	global_load_dwordx4 v[52:55], v[100:101], off nt
	global_load_dwordx4 v[56:59], v[102:103], off nt
	global_load_dwordx4 v[60:63], v[104:105], off nt
	global_load_dwordx4 v[64:67], v[106:107], off nt
	global_load_dwordx4 v[68:71], v[108:109], off nt
	global_load_dwordx4 v[72:75], v[110:111], off nt
	global_load_dwordx4 v[76:79], v[112:113], off nt
	global_load_dwordx4 v[80:83], v[114:115], off nt
	global_load_dwordx4 v[84:87], v[116:117], off nt
	global_load_dwordx4 v[88:91], v[118:119], off nt
	global_load_dwordx4 v[92:95], v[120:121], off nt
	global_load_dwordx4 v[96:99], v[122:123], off nt
	global_load_dwordx4 v[100:103], v[124:125], off nt
	global_load_dwordx4 v[104:107], v[126:127], off nt
	global_load_dwordx4 v[108:111], v[14:15], off nt
	v_add_u32_e32 v14, s6, v17
	v_ashrrev_i32_e32 v15, 31, v14
	v_lshlrev_b64 v[124:125], 11, v[14:15]
	v_add_u32_e32 v112, 8, v14
	v_lshl_add_u64 v[124:125], v[12:13], 0, v[124:125]
	v_ashrrev_i32_e32 v113, 31, v112
	v_lshlrev_b64 v[112:113], 11, v[112:113]
	v_add_u32_e32 v114, 16, v14
	v_lshl_add_u64 v[112:113], v[12:13], 0, v[112:113]
	v_ashrrev_i32_e32 v115, 31, v114
	v_lshlrev_b64 v[114:115], 11, v[114:115]
	v_add_u32_e32 v116, 24, v14
	v_lshl_add_u64 v[114:115], v[12:13], 0, v[114:115]
	v_ashrrev_i32_e32 v117, 31, v116
	v_lshlrev_b64 v[116:117], 11, v[116:117]
	v_add_u32_e32 v118, 32, v14
	v_lshl_add_u64 v[116:117], v[12:13], 0, v[116:117]
	v_ashrrev_i32_e32 v119, 31, v118
	v_lshlrev_b64 v[118:119], 11, v[118:119]
	v_add_u32_e32 v120, 40, v14
	v_lshl_add_u64 v[118:119], v[12:13], 0, v[118:119]
	v_ashrrev_i32_e32 v121, 31, v120
	v_lshlrev_b64 v[120:121], 11, v[120:121]
	s_waitcnt vmcnt(15)
	ds_write2_b32 v19, v2, v3 offset1:1
	ds_write2_b32 v19, v4, v5 offset0:2 offset1:3
	s_waitcnt vmcnt(14)
	ds_write2_b32 v20, v52, v53 offset1:1
	ds_write2_b32 v21, v54, v55 offset1:1
	s_waitcnt vmcnt(13)
	ds_write2_b32 v22, v56, v57 offset1:1
	ds_write2_b32 v23, v58, v59 offset1:1
	s_waitcnt vmcnt(12)
	ds_write2_b32 v24, v60, v61 offset1:1
	ds_write2_b32 v25, v62, v63 offset1:1
	s_waitcnt vmcnt(11)
	ds_write2_b32 v26, v64, v65 offset1:1
	ds_write2_b32 v27, v66, v67 offset1:1
	s_waitcnt vmcnt(10)
	ds_write2_b32 v28, v68, v69 offset1:1
	ds_write2_b32 v29, v70, v71 offset1:1
	s_waitcnt vmcnt(9)
	ds_write2_b32 v30, v72, v73 offset1:1
	ds_write2_b32 v31, v74, v75 offset1:1
	s_waitcnt vmcnt(8)
	ds_write2_b32 v32, v76, v77 offset1:1
	ds_write2_b32 v33, v78, v79 offset1:1
	s_waitcnt vmcnt(7)
	ds_write2_b32 v34, v80, v81 offset1:1
	ds_write2_b32 v35, v82, v83 offset1:1
	s_waitcnt vmcnt(6)
	ds_write2_b32 v36, v84, v85 offset1:1
	ds_write2_b32 v37, v86, v87 offset1:1
	s_waitcnt vmcnt(5)
	ds_write2_b32 v38, v88, v89 offset1:1
	ds_write2_b32 v39, v90, v91 offset1:1
	s_waitcnt vmcnt(4)
	ds_write2_b32 v40, v92, v93 offset1:1
	ds_write2_b32 v41, v94, v95 offset1:1
	s_waitcnt vmcnt(3)
	ds_write2_b32 v42, v96, v97 offset1:1
	ds_write2_b32 v43, v98, v99 offset1:1
	s_waitcnt vmcnt(2)
	ds_write2_b32 v44, v100, v101 offset1:1
	ds_write2_b32 v45, v102, v103 offset1:1
	s_waitcnt vmcnt(1)
	ds_write2_b32 v46, v104, v105 offset1:1
	ds_write2_b32 v47, v106, v107 offset1:1
	s_waitcnt vmcnt(0)
	ds_write2_b32 v48, v108, v109 offset1:1
	ds_write2_b32 v49, v110, v111 offset1:1
	s_waitcnt lgkmcnt(0)
	ds_read2_b32 v[2:3], v18 offset1:65
	s_waitcnt lgkmcnt(0)
	v_cvt_pk_bf16_f32 v2, v2, v3
	ds_read2_b32 v[4:5], v18 offset0:130 offset1:195
	s_waitcnt lgkmcnt(0)
	v_cvt_pk_bf16_f32 v3, v4, v5
	ds_read2_b32 v[4:5], v50 offset0:4 offset1:69
	s_waitcnt lgkmcnt(0)
	v_cvt_pk_bf16_f32 v4, v4, v5
	ds_read2_b32 v[52:53], v50 offset0:134 offset1:199
	s_waitcnt lgkmcnt(0)
	v_cvt_pk_bf16_f32 v5, v52, v53
	ds_read2_b32 v[52:53], v18 offset0:8 offset1:73
	global_store_dwordx4 v[124:125], v[2:5], off sc0 sc1
	v_add_u32_e32 v122, 48, v14
	v_lshl_add_u64 v[120:121], v[12:13], 0, v[120:121]
	s_waitcnt lgkmcnt(0)
	v_cvt_pk_bf16_f32 v2, v52, v53
	ds_read2_b32 v[4:5], v18 offset0:138 offset1:203
	s_waitcnt lgkmcnt(0)
	v_cvt_pk_bf16_f32 v3, v4, v5
	ds_read2_b32 v[4:5], v50 offset0:12 offset1:77
	s_waitcnt lgkmcnt(0)
	v_cvt_pk_bf16_f32 v4, v4, v5
	ds_read2_b32 v[52:53], v50 offset0:142 offset1:207
	s_waitcnt lgkmcnt(0)
	v_cvt_pk_bf16_f32 v5, v52, v53
	ds_read2_b32 v[52:53], v18 offset0:16 offset1:81
	global_store_dwordx4 v[112:113], v[2:5], off sc0 sc1
	v_ashrrev_i32_e32 v123, 31, v122
	v_lshlrev_b64 v[122:123], 11, v[122:123]
	s_waitcnt lgkmcnt(0)
	v_cvt_pk_bf16_f32 v2, v52, v53
	ds_read2_b32 v[4:5], v18 offset0:146 offset1:211
	s_waitcnt lgkmcnt(0)
	v_cvt_pk_bf16_f32 v3, v4, v5
	ds_read2_b32 v[4:5], v50 offset0:20 offset1:85
	s_waitcnt lgkmcnt(0)
	v_cvt_pk_bf16_f32 v4, v4, v5
	ds_read2_b32 v[52:53], v50 offset0:150 offset1:215
	s_waitcnt lgkmcnt(0)
	v_cvt_pk_bf16_f32 v5, v52, v53
	ds_read2_b32 v[52:53], v18 offset0:24 offset1:89
	global_store_dwordx4 v[114:115], v[2:5], off sc0 sc1
	v_add_u32_e32 v14, 56, v14
	v_lshl_add_u64 v[122:123], v[12:13], 0, v[122:123]
	s_waitcnt lgkmcnt(0)
	v_cvt_pk_bf16_f32 v2, v52, v53
	ds_read2_b32 v[4:5], v18 offset0:154 offset1:219
	s_waitcnt lgkmcnt(0)
	v_cvt_pk_bf16_f32 v3, v4, v5
	ds_read2_b32 v[4:5], v50 offset0:28 offset1:93
	s_waitcnt lgkmcnt(0)
	v_cvt_pk_bf16_f32 v4, v4, v5
	ds_read2_b32 v[52:53], v50 offset0:158 offset1:223
	s_waitcnt lgkmcnt(0)
	v_cvt_pk_bf16_f32 v5, v52, v53
	ds_read2_b32 v[52:53], v18 offset0:32 offset1:97
	global_store_dwordx4 v[116:117], v[2:5], off sc0 sc1
	v_ashrrev_i32_e32 v15, 31, v14
	v_lshlrev_b64 v[14:15], 11, v[14:15]
	s_waitcnt lgkmcnt(0)
	v_cvt_pk_bf16_f32 v2, v52, v53
	ds_read2_b32 v[4:5], v18 offset0:162 offset1:227
	s_waitcnt lgkmcnt(0)
	v_cvt_pk_bf16_f32 v3, v4, v5
	ds_read2_b32 v[4:5], v50 offset0:36 offset1:101
	s_waitcnt lgkmcnt(0)
	v_cvt_pk_bf16_f32 v4, v4, v5
	ds_read2_b32 v[52:53], v50 offset0:166 offset1:231
	s_waitcnt lgkmcnt(0)
	v_cvt_pk_bf16_f32 v5, v52, v53
	ds_read2_b32 v[52:53], v18 offset0:40 offset1:105
	global_store_dwordx4 v[118:119], v[2:5], off sc0 sc1
	v_lshl_add_u64 v[12:13], v[12:13], 0, v[14:15]
	s_waitcnt lgkmcnt(0)
	v_cvt_pk_bf16_f32 v2, v52, v53
	ds_read2_b32 v[4:5], v18 offset0:170 offset1:235
	s_waitcnt lgkmcnt(0)
	v_cvt_pk_bf16_f32 v3, v4, v5
	ds_read2_b32 v[4:5], v50 offset0:44 offset1:109
	s_waitcnt lgkmcnt(0)
	v_cvt_pk_bf16_f32 v4, v4, v5
	ds_read2_b32 v[52:53], v50 offset0:174 offset1:239
	s_waitcnt lgkmcnt(0)
	v_cvt_pk_bf16_f32 v5, v52, v53
	ds_read2_b32 v[52:53], v18 offset0:48 offset1:113
	global_store_dwordx4 v[120:121], v[2:5], off sc0 sc1
	s_waitcnt lgkmcnt(0)
	s_nop 0
	v_cvt_pk_bf16_f32 v2, v52, v53
	ds_read2_b32 v[4:5], v18 offset0:178 offset1:243
	s_waitcnt lgkmcnt(0)
	v_cvt_pk_bf16_f32 v3, v4, v5
	ds_read2_b32 v[4:5], v50 offset0:52 offset1:117
	s_waitcnt lgkmcnt(0)
	v_cvt_pk_bf16_f32 v4, v4, v5
	ds_read2_b32 v[52:53], v50 offset0:182 offset1:247
	s_waitcnt lgkmcnt(0)
	v_cvt_pk_bf16_f32 v5, v52, v53
	ds_read2_b32 v[52:53], v18 offset0:56 offset1:121
	global_store_dwordx4 v[122:123], v[2:5], off sc0 sc1
	s_waitcnt lgkmcnt(0)
	s_nop 0
	v_cvt_pk_bf16_f32 v2, v52, v53
	ds_read2_b32 v[4:5], v18 offset0:186 offset1:251
	s_waitcnt lgkmcnt(0)
	v_cvt_pk_bf16_f32 v3, v4, v5
	ds_read2_b32 v[4:5], v50 offset0:60 offset1:125
	s_waitcnt lgkmcnt(0)
	v_cvt_pk_bf16_f32 v4, v4, v5
	ds_read2_b32 v[52:53], v50 offset0:190 offset1:255
	s_waitcnt lgkmcnt(0)
	v_cvt_pk_bf16_f32 v5, v52, v53
	global_store_dwordx4 v[12:13], v[2:5], off sc0 sc1
	s_waitcnt lgkmcnt(0)
	s_cbranch_scc0 .LBB0_22

.LBB0_170:
	v_mul_f32_e32 v149, 0xbfb8aa3b, v126
	v_exp_f32_e32 v149, v149
	v_lshl_or_b32 v150, s34, 7, v146
	v_lshl_add_u32 v148, s36, 8, v144
	v_ashrrev_i32_e32 v151, 31, v150
	v_add_f32_e32 v149, 1.0, v149
	v_rcp_f32_e32 v149, v149
	v_mov_b64_e32 v[142:143], s[20:21]
	v_mad_i64_i32 v[152:153], s[34:35], v148, s47, v[142:143]
	v_mul_f32_e32 v126, v126, v149
	v_mul_f32_e32 v122, v126, v122
	v_mul_f32_e32 v126, 0xbfb8aa3b, v127
	v_exp_f32_e32 v126, v126
	s_andn2_b64 vcc, exec, s[4:5]
	s_movk_i32 s65, 0xff5d
	s_movk_i32 s64, 0xff7c
	v_add_f32_e32 v126, 1.0, v126
	v_rcp_f32_e32 v126, v126
	s_nop 0
	v_mul_f32_e32 v126, v127, v126
	v_mul_f32_e32 v123, v126, v123
	v_mul_f32_e32 v126, 0xbfb8aa3b, v128
	v_exp_f32_e32 v126, v126
	s_nop 0
	v_add_f32_e32 v126, 1.0, v126
	v_rcp_f32_e32 v126, v126
	s_nop 0
	v_mul_f32_e32 v126, v128, v126
	v_mul_f32_e32 v124, v126, v124
	v_mul_f32_e32 v126, 0xbfb8aa3b, v129
	v_exp_f32_e32 v126, v126
	s_nop 0
	v_add_f32_e32 v126, 1.0, v126
	v_rcp_f32_e32 v126, v126
	s_nop 0
	v_mul_f32_e32 v126, v129, v126
	v_mul_f32_e32 v125, v126, v125
	v_mul_f32_e32 v126, 0xbfb8aa3b, v118
	v_exp_f32_e32 v126, v126
	s_nop 0
	v_add_f32_e32 v126, 1.0, v126
	v_rcp_f32_e32 v126, v126
	s_nop 0
	v_mul_f32_e32 v118, v118, v126
	v_mul_f32_e32 v118, v118, v114
	v_mul_f32_e32 v114, 0xbfb8aa3b, v119
	v_exp_f32_e32 v114, v114
	s_nop 0
	v_add_f32_e32 v114, 1.0, v114
	v_rcp_f32_e32 v114, v114
	s_nop 0
	v_mul_f32_e32 v114, v119, v114
	v_mul_f32_e32 v119, v114, v115
	v_mul_f32_e32 v114, 0xbfb8aa3b, v120
	v_exp_f32_e32 v114, v114
	s_nop 0
	v_add_f32_e32 v114, 1.0, v114
	v_rcp_f32_e32 v114, v114
	s_nop 0
	v_mul_f32_e32 v114, v120, v114
	v_mul_f32_e32 v126, v114, v116
	v_mul_f32_e32 v114, 0xbfb8aa3b, v121
	v_exp_f32_e32 v114, v114
	v_cvt_pk_bf16_f32 v116, v122, v123
	s_nop 0
	v_add_f32_e32 v114, 1.0, v114
	v_rcp_f32_e32 v114, v114
	s_nop 0
	v_mul_f32_e32 v114, v121, v114
	v_mul_f32_e32 v127, v114, v117
	v_lshlrev_b64 v[114:115], 1, v[150:151]
	v_lshl_add_u64 v[120:121], v[152:153], 0, v[114:115]
	v_cvt_pk_bf16_f32 v117, v124, v125
	v_cvt_pk_bf16_f32 v118, v118, v119
	v_cvt_pk_bf16_f32 v119, v126, v127
	global_store_dwordx4 v[120:121], v[116:119], off sc0 sc1
	s_nop 1
	v_mul_f32_e32 v118, 0xbfb8aa3b, v110
	v_exp_f32_e32 v118, v118
	v_or_b32_e32 v116, 16, v148
	v_mad_i64_i32 v[116:117], s[34:35], v116, s47, v[142:143]
	v_add_f32_e32 v118, 1.0, v118
	v_rcp_f32_e32 v118, v118
	s_nop 0
	v_mul_f32_e32 v110, v110, v118
	v_mul_f32_e32 v106, v110, v106
	v_mul_f32_e32 v110, 0xbfb8aa3b, v111
	v_exp_f32_e32 v110, v110
	s_nop 0
	v_add_f32_e32 v110, 1.0, v110
	v_rcp_f32_e32 v110, v110
	s_nop 0
	v_mul_f32_e32 v110, v111, v110
	v_mul_f32_e32 v107, v110, v107
	v_mul_f32_e32 v110, 0xbfb8aa3b, v112
	v_exp_f32_e32 v110, v110
	s_nop 0
	v_add_f32_e32 v110, 1.0, v110
	v_rcp_f32_e32 v110, v110
	s_nop 0
	v_mul_f32_e32 v110, v112, v110
	v_mul_f32_e32 v108, v110, v108
	v_mul_f32_e32 v110, 0xbfb8aa3b, v113
	v_exp_f32_e32 v110, v110
	s_nop 0
	v_add_f32_e32 v110, 1.0, v110
	v_rcp_f32_e32 v110, v110
	s_nop 0
	v_mul_f32_e32 v110, v113, v110
	v_mul_f32_e32 v109, v110, v109
	v_mul_f32_e32 v110, 0xbfb8aa3b, v102
	v_exp_f32_e32 v110, v110
	s_nop 0
	v_add_f32_e32 v110, 1.0, v110
	v_rcp_f32_e32 v110, v110
	s_nop 0
	v_mul_f32_e32 v102, v102, v110
	v_mul_f32_e32 v110, v102, v98
	v_mul_f32_e32 v98, 0xbfb8aa3b, v103
	v_exp_f32_e32 v98, v98
	s_nop 0
	v_add_f32_e32 v98, 1.0, v98
	v_rcp_f32_e32 v98, v98
	s_nop 0
	v_mul_f32_e32 v98, v103, v98
	v_mul_f32_e32 v111, v98, v99
	v_mul_f32_e32 v98, 0xbfb8aa3b, v104
	v_exp_f32_e32 v98, v98
	v_lshl_add_u64 v[102:103], v[116:117], 0, v[114:115]
	v_add_f32_e32 v98, 1.0, v98
	v_rcp_f32_e32 v98, v98
	s_nop 0
	v_mul_f32_e32 v98, v104, v98
	v_mul_f32_e32 v104, v98, v100
	v_mul_f32_e32 v98, 0xbfb8aa3b, v105
	v_exp_f32_e32 v98, v98
	s_nop 0
	v_add_f32_e32 v98, 1.0, v98
	v_rcp_f32_e32 v98, v98
	s_nop 0
	v_mul_f32_e32 v98, v105, v98
	v_mul_f32_e32 v101, v98, v101
	v_cvt_pk_bf16_f32 v98, v106, v107
	v_cvt_pk_bf16_f32 v99, v108, v109
	v_cvt_pk_bf16_f32 v100, v110, v111
	v_cvt_pk_bf16_f32 v101, v104, v101
	global_store_dwordx4 v[102:103], v[98:101], off sc0 sc1
	s_nop 1
	v_mul_f32_e32 v100, 0xbfb8aa3b, v94
	v_exp_f32_e32 v100, v100
	v_or_b32_e32 v98, 32, v148
	v_mad_i64_i32 v[98:99], s[34:35], v98, s47, v[142:143]
	v_add_f32_e32 v100, 1.0, v100
	v_rcp_f32_e32 v100, v100
	s_nop 0
	v_mul_f32_e32 v94, v94, v100
	v_mul_f32_e32 v90, v94, v90
	v_mul_f32_e32 v94, 0xbfb8aa3b, v95
	v_exp_f32_e32 v94, v94
	s_nop 0
	v_add_f32_e32 v94, 1.0, v94
	v_rcp_f32_e32 v94, v94
	s_nop 0
	v_mul_f32_e32 v94, v95, v94
	v_mul_f32_e32 v91, v94, v91
	v_mul_f32_e32 v94, 0xbfb8aa3b, v96
	v_exp_f32_e32 v94, v94
	s_nop 0
	v_add_f32_e32 v94, 1.0, v94
	v_rcp_f32_e32 v94, v94
	s_nop 0
	v_mul_f32_e32 v94, v96, v94
	v_mul_f32_e32 v92, v94, v92
	v_mul_f32_e32 v94, 0xbfb8aa3b, v97
	v_exp_f32_e32 v94, v94
	s_nop 0
	v_add_f32_e32 v94, 1.0, v94
	v_rcp_f32_e32 v94, v94
	s_nop 0
	v_mul_f32_e32 v94, v97, v94
	v_mul_f32_e32 v93, v94, v93
	v_mul_f32_e32 v94, 0xbfb8aa3b, v86
	v_exp_f32_e32 v94, v94
	s_nop 0
	v_add_f32_e32 v94, 1.0, v94
	v_rcp_f32_e32 v94, v94
	s_nop 0
	v_mul_f32_e32 v86, v86, v94
	v_mul_f32_e32 v94, v86, v82
	v_mul_f32_e32 v82, 0xbfb8aa3b, v87
	v_exp_f32_e32 v82, v82
	s_nop 0
	v_add_f32_e32 v82, 1.0, v82
	v_rcp_f32_e32 v82, v82
	s_nop 0
	v_mul_f32_e32 v82, v87, v82
	v_mul_f32_e32 v95, v82, v83
	v_mul_f32_e32 v82, 0xbfb8aa3b, v88
	v_exp_f32_e32 v82, v82
	v_lshl_add_u64 v[86:87], v[98:99], 0, v[114:115]
	v_add_f32_e32 v82, 1.0, v82
	v_rcp_f32_e32 v82, v82
	s_nop 0
	v_mul_f32_e32 v82, v88, v82
	v_mul_f32_e32 v88, v82, v84
	v_mul_f32_e32 v82, 0xbfb8aa3b, v89
	v_exp_f32_e32 v82, v82
	s_nop 0
	v_add_f32_e32 v82, 1.0, v82
	v_rcp_f32_e32 v82, v82
	s_nop 0
	v_mul_f32_e32 v82, v89, v82
	v_mul_f32_e32 v85, v82, v85
	v_cvt_pk_bf16_f32 v82, v90, v91
	v_cvt_pk_bf16_f32 v83, v92, v93
	v_cvt_pk_bf16_f32 v84, v94, v95
	v_cvt_pk_bf16_f32 v85, v88, v85
	global_store_dwordx4 v[86:87], v[82:85], off sc0 sc1
	s_nop 1
	v_mul_f32_e32 v84, 0xbfb8aa3b, v78
	v_exp_f32_e32 v84, v84
	v_or_b32_e32 v82, 48, v148
	v_mad_i64_i32 v[82:83], s[34:35], v82, s47, v[142:143]
	v_add_f32_e32 v84, 1.0, v84
	v_rcp_f32_e32 v84, v84
	s_nop 0
	v_mul_f32_e32 v78, v78, v84
	v_mul_f32_e32 v74, v78, v74
	v_mul_f32_e32 v78, 0xbfb8aa3b, v79
	v_exp_f32_e32 v78, v78
	s_nop 0
	v_add_f32_e32 v78, 1.0, v78
	v_rcp_f32_e32 v78, v78
	s_nop 0
	v_mul_f32_e32 v78, v79, v78
	v_mul_f32_e32 v75, v78, v75
	v_mul_f32_e32 v78, 0xbfb8aa3b, v80
	v_exp_f32_e32 v78, v78
	s_nop 0
	v_add_f32_e32 v78, 1.0, v78
	v_rcp_f32_e32 v78, v78
	s_nop 0
	v_mul_f32_e32 v78, v80, v78
	v_mul_f32_e32 v76, v78, v76
	v_mul_f32_e32 v78, 0xbfb8aa3b, v81
	v_exp_f32_e32 v78, v78
	s_nop 0
	v_add_f32_e32 v78, 1.0, v78
	v_rcp_f32_e32 v78, v78
	s_nop 0
	v_mul_f32_e32 v78, v81, v78
	v_mul_f32_e32 v77, v78, v77
	v_mul_f32_e32 v78, 0xbfb8aa3b, v70
	v_exp_f32_e32 v78, v78
	s_nop 0
	v_add_f32_e32 v78, 1.0, v78
	v_rcp_f32_e32 v78, v78
	s_nop 0
	v_mul_f32_e32 v70, v70, v78
	v_mul_f32_e32 v78, v70, v66
	v_mul_f32_e32 v66, 0xbfb8aa3b, v71
	v_exp_f32_e32 v66, v66
	s_nop 0
	v_add_f32_e32 v66, 1.0, v66
	v_rcp_f32_e32 v66, v66
	s_nop 0
	v_mul_f32_e32 v66, v71, v66
	v_mul_f32_e32 v79, v66, v67
	v_mul_f32_e32 v66, 0xbfb8aa3b, v72
	v_exp_f32_e32 v66, v66
	v_lshl_add_u64 v[70:71], v[82:83], 0, v[114:115]
	v_add_f32_e32 v66, 1.0, v66
	v_rcp_f32_e32 v66, v66
	s_nop 0
	v_mul_f32_e32 v66, v72, v66
	v_mul_f32_e32 v72, v66, v68
	v_mul_f32_e32 v66, 0xbfb8aa3b, v73
	v_exp_f32_e32 v66, v66
	s_nop 0
	v_add_f32_e32 v66, 1.0, v66
	v_rcp_f32_e32 v66, v66
	s_nop 0
	v_mul_f32_e32 v66, v73, v66
	v_mul_f32_e32 v69, v66, v69
	v_cvt_pk_bf16_f32 v66, v74, v75
	v_cvt_pk_bf16_f32 v67, v76, v77
	v_cvt_pk_bf16_f32 v68, v78, v79
	v_cvt_pk_bf16_f32 v69, v72, v69
	global_store_dwordx4 v[70:71], v[66:69], off sc0 sc1
	s_nop 1
	v_mul_f32_e32 v68, 0xbfb8aa3b, v62
	v_exp_f32_e32 v68, v68
	v_add_u32_e32 v66, 0x80, v148
	v_mad_i64_i32 v[66:67], s[34:35], v66, s47, v[142:143]
	v_add_f32_e32 v68, 1.0, v68
	v_rcp_f32_e32 v68, v68
	s_nop 0
	v_mul_f32_e32 v62, v62, v68
	v_mul_f32_e32 v58, v62, v58
	v_mul_f32_e32 v62, 0xbfb8aa3b, v63
	v_exp_f32_e32 v62, v62
	s_nop 0
	v_add_f32_e32 v62, 1.0, v62
	v_rcp_f32_e32 v62, v62
	s_nop 0
	v_mul_f32_e32 v62, v63, v62
	v_mul_f32_e32 v59, v62, v59
	v_mul_f32_e32 v62, 0xbfb8aa3b, v64
	v_exp_f32_e32 v62, v62
	s_nop 0
	v_add_f32_e32 v62, 1.0, v62
	v_rcp_f32_e32 v62, v62
	s_nop 0
	v_mul_f32_e32 v62, v64, v62
	v_mul_f32_e32 v60, v62, v60
	v_mul_f32_e32 v62, 0xbfb8aa3b, v65
	v_exp_f32_e32 v62, v62
	s_nop 0
	v_add_f32_e32 v62, 1.0, v62
	v_rcp_f32_e32 v62, v62
	s_nop 0
	v_mul_f32_e32 v62, v65, v62
	v_mul_f32_e32 v61, v62, v61
	v_mul_f32_e32 v62, 0xbfb8aa3b, v54
	v_exp_f32_e32 v62, v62
	s_nop 0
	v_add_f32_e32 v62, 1.0, v62
	v_rcp_f32_e32 v62, v62
	s_nop 0
	v_mul_f32_e32 v54, v54, v62
	v_mul_f32_e32 v62, v54, v50
	v_mul_f32_e32 v50, 0xbfb8aa3b, v55
	v_exp_f32_e32 v50, v50
	s_nop 0
	v_add_f32_e32 v50, 1.0, v50
	v_rcp_f32_e32 v50, v50
	s_nop 0
	v_mul_f32_e32 v50, v55, v50
	v_mul_f32_e32 v63, v50, v51
	v_mul_f32_e32 v50, 0xbfb8aa3b, v56
	v_exp_f32_e32 v50, v50
	v_lshl_add_u64 v[54:55], v[66:67], 0, v[114:115]
	v_add_f32_e32 v50, 1.0, v50
	v_rcp_f32_e32 v50, v50
	s_nop 0
	v_mul_f32_e32 v50, v56, v50
	v_mul_f32_e32 v56, v50, v52
	v_mul_f32_e32 v50, 0xbfb8aa3b, v57
	v_exp_f32_e32 v50, v50
	s_nop 0
	v_add_f32_e32 v50, 1.0, v50
	v_rcp_f32_e32 v50, v50
	s_nop 0
	v_mul_f32_e32 v50, v57, v50
	v_mul_f32_e32 v53, v50, v53
	v_cvt_pk_bf16_f32 v50, v58, v59
	v_cvt_pk_bf16_f32 v51, v60, v61
	v_cvt_pk_bf16_f32 v52, v62, v63
	v_cvt_pk_bf16_f32 v53, v56, v53
	global_store_dwordx4 v[54:55], v[50:53], off sc0 sc1
	s_nop 1
	v_mul_f32_e32 v52, 0xbfb8aa3b, v46
	v_exp_f32_e32 v52, v52
	v_add_u32_e32 v50, 0x90, v148
	v_mad_i64_i32 v[50:51], s[34:35], v50, s47, v[142:143]
	v_add_f32_e32 v52, 1.0, v52
	v_rcp_f32_e32 v52, v52
	s_nop 0
	v_mul_f32_e32 v46, v46, v52
	v_mul_f32_e32 v42, v46, v42
	v_mul_f32_e32 v46, 0xbfb8aa3b, v47
	v_exp_f32_e32 v46, v46
	s_nop 0
	v_add_f32_e32 v46, 1.0, v46
	v_rcp_f32_e32 v46, v46
	s_nop 0
	v_mul_f32_e32 v46, v47, v46
	v_mul_f32_e32 v43, v46, v43
	v_mul_f32_e32 v46, 0xbfb8aa3b, v48
	v_exp_f32_e32 v46, v46
	s_nop 0
	v_add_f32_e32 v46, 1.0, v46
	v_rcp_f32_e32 v46, v46
	s_nop 0
	v_mul_f32_e32 v46, v48, v46
	v_mul_f32_e32 v44, v46, v44
	v_mul_f32_e32 v46, 0xbfb8aa3b, v49
	v_exp_f32_e32 v46, v46
	s_nop 0
	v_add_f32_e32 v46, 1.0, v46
	v_rcp_f32_e32 v46, v46
	s_nop 0
	v_mul_f32_e32 v46, v49, v46
	v_mul_f32_e32 v45, v46, v45
	v_mul_f32_e32 v46, 0xbfb8aa3b, v38
	v_exp_f32_e32 v46, v46
	s_nop 0
	v_add_f32_e32 v46, 1.0, v46
	v_rcp_f32_e32 v46, v46
	s_nop 0
	v_mul_f32_e32 v38, v38, v46
	v_mul_f32_e32 v46, v38, v34
	v_mul_f32_e32 v34, 0xbfb8aa3b, v39
	v_exp_f32_e32 v34, v34
	s_nop 0
	v_add_f32_e32 v34, 1.0, v34
	v_rcp_f32_e32 v34, v34
	s_nop 0
	v_mul_f32_e32 v34, v39, v34
	v_mul_f32_e32 v47, v34, v35
	v_mul_f32_e32 v34, 0xbfb8aa3b, v40
	v_exp_f32_e32 v34, v34
	v_lshl_add_u64 v[38:39], v[50:51], 0, v[114:115]
	v_add_f32_e32 v34, 1.0, v34
	v_rcp_f32_e32 v34, v34
	s_nop 0
	v_mul_f32_e32 v34, v40, v34
	v_mul_f32_e32 v40, v34, v36
	v_mul_f32_e32 v34, 0xbfb8aa3b, v41
	v_exp_f32_e32 v34, v34
	s_nop 0
	v_add_f32_e32 v34, 1.0, v34
	v_rcp_f32_e32 v34, v34
	s_nop 0
	v_mul_f32_e32 v34, v41, v34
	v_mul_f32_e32 v37, v34, v37
	v_cvt_pk_bf16_f32 v34, v42, v43
	v_cvt_pk_bf16_f32 v35, v44, v45
	v_cvt_pk_bf16_f32 v36, v46, v47
	v_cvt_pk_bf16_f32 v37, v40, v37
	global_store_dwordx4 v[38:39], v[34:37], off sc0 sc1
	s_nop 1
	v_mul_f32_e32 v36, 0xbfb8aa3b, v30
	v_exp_f32_e32 v36, v36
	v_add_u32_e32 v34, 0xa0, v148
	v_mad_i64_i32 v[34:35], s[34:35], v34, s47, v[142:143]
	v_add_f32_e32 v36, 1.0, v36
	v_rcp_f32_e32 v36, v36
	s_nop 0
	v_mul_f32_e32 v30, v30, v36
	v_mul_f32_e32 v26, v30, v26
	v_mul_f32_e32 v30, 0xbfb8aa3b, v31
	v_exp_f32_e32 v30, v30
	s_nop 0
	v_add_f32_e32 v30, 1.0, v30
	v_rcp_f32_e32 v30, v30
	s_nop 0
	v_mul_f32_e32 v30, v31, v30
	v_mul_f32_e32 v27, v30, v27
	v_mul_f32_e32 v30, 0xbfb8aa3b, v32
	v_exp_f32_e32 v30, v30
	s_nop 0
	v_add_f32_e32 v30, 1.0, v30
	v_rcp_f32_e32 v30, v30
	s_nop 0
	v_mul_f32_e32 v30, v32, v30
	v_mul_f32_e32 v28, v30, v28
	v_mul_f32_e32 v30, 0xbfb8aa3b, v33
	v_exp_f32_e32 v30, v30
	s_nop 0
	v_add_f32_e32 v30, 1.0, v30
	v_rcp_f32_e32 v30, v30
	s_nop 0
	v_mul_f32_e32 v30, v33, v30
	v_mul_f32_e32 v29, v30, v29
	v_mul_f32_e32 v30, 0xbfb8aa3b, v22
	v_exp_f32_e32 v30, v30
	s_nop 0
	v_add_f32_e32 v30, 1.0, v30
	v_rcp_f32_e32 v30, v30
	s_nop 0
	v_mul_f32_e32 v22, v22, v30
	v_mul_f32_e32 v30, v22, v18
	v_mul_f32_e32 v18, 0xbfb8aa3b, v23
	v_exp_f32_e32 v18, v18
	s_nop 0
	v_add_f32_e32 v18, 1.0, v18
	v_rcp_f32_e32 v18, v18
	s_nop 0
	v_mul_f32_e32 v18, v23, v18
	v_mul_f32_e32 v31, v18, v19
	v_mul_f32_e32 v18, 0xbfb8aa3b, v24
	v_exp_f32_e32 v18, v18
	v_lshl_add_u64 v[22:23], v[34:35], 0, v[114:115]
	v_add_f32_e32 v18, 1.0, v18
	v_rcp_f32_e32 v18, v18
	s_nop 0
	v_mul_f32_e32 v18, v24, v18
	v_mul_f32_e32 v24, v18, v20
	v_mul_f32_e32 v18, 0xbfb8aa3b, v25
	v_exp_f32_e32 v18, v18
	s_nop 0
	v_add_f32_e32 v18, 1.0, v18
	v_rcp_f32_e32 v18, v18
	s_nop 0
	v_mul_f32_e32 v18, v25, v18
	v_mul_f32_e32 v21, v18, v21
	v_cvt_pk_bf16_f32 v18, v26, v27
	v_cvt_pk_bf16_f32 v19, v28, v29
	v_cvt_pk_bf16_f32 v20, v30, v31
	v_cvt_pk_bf16_f32 v21, v24, v21
	global_store_dwordx4 v[22:23], v[18:21], off sc0 sc1
	s_nop 1
	v_mul_f32_e32 v20, 0xbfb8aa3b, v14
	v_exp_f32_e32 v20, v20
	v_add_u32_e32 v18, 0xb0, v148
	v_mad_i64_i32 v[18:19], s[34:35], v18, s47, v[142:143]
	v_add_f32_e32 v20, 1.0, v20
	v_rcp_f32_e32 v20, v20
	s_mov_b64 s[34:35], -1
	v_mul_f32_e32 v14, v14, v20
	v_mul_f32_e32 v10, v14, v10
	v_mul_f32_e32 v14, 0xbfb8aa3b, v15
	v_exp_f32_e32 v14, v14
	s_nop 0
	v_add_f32_e32 v14, 1.0, v14
	v_rcp_f32_e32 v14, v14
	s_nop 0
	v_mul_f32_e32 v14, v15, v14
	v_mul_f32_e32 v11, v14, v11
	v_mul_f32_e32 v14, 0xbfb8aa3b, v16
	v_exp_f32_e32 v14, v14
	s_nop 0
	v_add_f32_e32 v14, 1.0, v14
	v_rcp_f32_e32 v14, v14
	s_nop 0
	v_mul_f32_e32 v14, v16, v14
	v_mul_f32_e32 v12, v14, v12
	v_mul_f32_e32 v14, 0xbfb8aa3b, v17
	v_exp_f32_e32 v14, v14
	s_nop 0
	v_add_f32_e32 v14, 1.0, v14
	v_rcp_f32_e32 v14, v14
	s_nop 0
	v_mul_f32_e32 v14, v17, v14
	v_mul_f32_e32 v13, v14, v13
	v_mul_f32_e32 v14, 0xbfb8aa3b, v6
	v_exp_f32_e32 v14, v14
	s_nop 0
	v_add_f32_e32 v14, 1.0, v14
	v_rcp_f32_e32 v14, v14
	s_nop 0
	v_mul_f32_e32 v6, v6, v14
	v_mul_f32_e32 v14, v6, v2
	v_mul_f32_e32 v2, 0xbfb8aa3b, v7
	v_exp_f32_e32 v2, v2
	s_nop 0
	v_add_f32_e32 v2, 1.0, v2
	v_rcp_f32_e32 v2, v2
	s_nop 0
	v_mul_f32_e32 v2, v7, v2
	v_mul_f32_e32 v15, v2, v3
	v_mul_f32_e32 v2, 0xbfb8aa3b, v8
	v_exp_f32_e32 v2, v2
	v_lshl_add_u64 v[6:7], v[18:19], 0, v[114:115]
	v_add_f32_e32 v2, 1.0, v2
	v_rcp_f32_e32 v2, v2
	s_nop 0
	v_mul_f32_e32 v2, v8, v2
	v_mul_f32_e32 v8, v2, v4
	v_mul_f32_e32 v2, 0xbfb8aa3b, v9
	v_exp_f32_e32 v2, v2
	s_nop 0
	v_add_f32_e32 v2, 1.0, v2
	v_rcp_f32_e32 v2, v2
	s_nop 0
	v_mul_f32_e32 v2, v9, v2
	v_mul_f32_e32 v5, v2, v5
	v_cvt_pk_bf16_f32 v2, v10, v11
	v_cvt_pk_bf16_f32 v3, v12, v13
	v_cvt_pk_bf16_f32 v4, v14, v15
	v_cvt_pk_bf16_f32 v5, v8, v5
	global_store_dwordx4 v[6:7], v[2:5], off sc0 sc1
	s_cbranch_vccnz .LBB0_163
	s_andn2_b64 vcc, exec, s[12:13]
	s_cbranch_vccnz .LBB0_162
	s_barrier
	s_branch .LBB0_162

.LBB0_178:
	s_lshl_b32 s78, s15, 6
	v_add_u32_e32 v3, s78, v6
	v_mad_i64_i32 v[4:5], s[42:43], v3, s2, 0
	s_waitcnt lgkmcnt(0)
	v_lshl_add_u64 v[4:5], v[4:5], 2, s[64:65]
	s_ashr_i32 s53, s52, 31
	v_lshl_add_u64 v[4:5], s[52:53], 2, v[4:5]
	v_lshl_add_u64 v[4:5], v[4:5], 0, v[0:1]
	s_lshl_b32 s66, s2, 4
	v_lshl_add_u64 v[14:15], v[4:5], 0, s[66:67]
	global_load_dwordx4 v[10:13], v[4:5], off nt
	s_lshl_b32 s66, s2, 5
	global_load_dwordx4 v[14:17], v[14:15], off nt
	v_lshl_add_u64 v[18:19], v[4:5], 0, s[66:67]
	global_load_dwordx4 v[18:21], v[18:19], off nt
	s_mul_i32 s66, s2, 48
	v_lshl_add_u64 v[22:23], v[4:5], 0, s[66:67]
	global_load_dwordx4 v[22:25], v[22:23], off nt
	s_lshl_b32 s66, s2, 6
	v_lshl_add_u64 v[26:27], v[4:5], 0, s[66:67]
	global_load_dwordx4 v[26:29], v[26:27], off nt
	s_mul_i32 s66, s2, 0x50
	v_lshl_add_u64 v[30:31], v[4:5], 0, s[66:67]
	global_load_dwordx4 v[30:33], v[30:31], off nt
	s_mul_i32 s66, s2, 0x60
	v_lshl_add_u64 v[34:35], v[4:5], 0, s[66:67]
	global_load_dwordx4 v[34:37], v[34:35], off nt
	s_mul_i32 s66, s2, 0x70
	v_lshl_add_u64 v[38:39], v[4:5], 0, s[66:67]
	global_load_dwordx4 v[38:41], v[38:39], off nt
	s_lshl_b32 s66, s2, 7
	v_lshl_add_u64 v[42:43], v[4:5], 0, s[66:67]
	global_load_dwordx4 v[42:45], v[42:43], off nt
	s_mul_i32 s66, s2, 0x90
	v_lshl_add_u64 v[46:47], v[4:5], 0, s[66:67]
	global_load_dwordx4 v[46:49], v[46:47], off nt
	s_mul_i32 s66, s2, 0xa0
	v_lshl_add_u64 v[50:51], v[4:5], 0, s[66:67]
	global_load_dwordx4 v[50:53], v[50:51], off nt
	s_mul_i32 s66, s2, 0xb0
	v_lshl_add_u64 v[54:55], v[4:5], 0, s[66:67]
	global_load_dwordx4 v[54:57], v[54:55], off nt
	s_mul_i32 s66, s2, 0xc0
	v_lshl_add_u64 v[58:59], v[4:5], 0, s[66:67]
	global_load_dwordx4 v[58:61], v[58:59], off nt
	s_mul_i32 s66, s2, 0xd0
	v_lshl_add_u64 v[62:63], v[4:5], 0, s[66:67]
	global_load_dwordx4 v[62:65], v[62:63], off nt
	s_mul_i32 s66, s2, 0xe0
	s_waitcnt vmcnt(0)
	v_lshl_add_u64 v[66:67], v[4:5], 0, s[66:67]
	global_load_dwordx4 v[66:69], v[66:67], off nt
	s_mul_i32 s66, s2, 0xf0
	v_lshl_add_u64 v[4:5], v[4:5], 0, s[66:67]
	global_load_dwordx4 v[70:73], v[4:5], off nt
	v_add_u32_e32 v3, 0x410, v9
	s_ashr_i32 s79, s78, 31
	s_lshl_b64 s[42:43], s[78:79], 1
	s_add_u32 s42, s62, s42
	s_addc_u32 s43, s63, s43
	v_readlane_b32 s2, v254, 31
	s_add_i32 s12, s12, s2
	s_cmp_lt_i32 s12, s7
	s_waitcnt vmcnt(0)
	ds_write2_b32 v9, v10, v11 offset1:1
	ds_write2_b32 v9, v12, v13 offset0:2 offset1:3
	ds_write2_b32 v3, v14, v15 offset1:1
	v_add_u32_e32 v3, 0x418, v9
	ds_write2_b32 v3, v16, v17 offset1:1
	v_add_u32_e32 v3, 0x820, v9
	ds_write2_b32 v3, v18, v19 offset1:1
	v_add_u32_e32 v3, 0x828, v9
	ds_write2_b32 v3, v20, v21 offset1:1
	v_add_u32_e32 v3, 0xc30, v9
	ds_write2_b32 v3, v22, v23 offset1:1
	v_add_u32_e32 v3, 0xc38, v9
	ds_write2_b32 v3, v24, v25 offset1:1
	v_add_u32_e32 v3, 0x1040, v9
	ds_write2_b32 v3, v26, v27 offset1:1
	v_add_u32_e32 v3, 0x1048, v9
	ds_write2_b32 v3, v28, v29 offset1:1
	v_add_u32_e32 v3, 0x1450, v9
	ds_write2_b32 v3, v30, v31 offset1:1
	v_add_u32_e32 v3, 0x1458, v9
	ds_write2_b32 v3, v32, v33 offset1:1
	v_add_u32_e32 v3, 0x1860, v9
	ds_write2_b32 v3, v34, v35 offset1:1
	v_add_u32_e32 v3, 0x1868, v9
	ds_write2_b32 v3, v36, v37 offset1:1
	v_add_u32_e32 v3, 0x1c70, v9
	ds_write2_b32 v3, v38, v39 offset1:1
	v_add_u32_e32 v3, 0x1c78, v9
	ds_write2_b32 v3, v40, v41 offset1:1
	v_add_u32_e32 v3, 0x2080, v9
	ds_write2_b32 v3, v42, v43 offset1:1
	v_add_u32_e32 v3, 0x2088, v9
	ds_write2_b32 v3, v44, v45 offset1:1
	v_add_u32_e32 v3, 0x2490, v9
	ds_write2_b32 v3, v46, v47 offset1:1
	v_add_u32_e32 v3, 0x2498, v9
	ds_write2_b32 v3, v48, v49 offset1:1
	v_add_u32_e32 v3, 0x28a0, v9
	ds_write2_b32 v3, v50, v51 offset1:1
	v_add_u32_e32 v3, 0x28a8, v9
	ds_write2_b32 v3, v52, v53 offset1:1
	v_add_u32_e32 v3, 0x2cb0, v9
	ds_write2_b32 v3, v54, v55 offset1:1
	v_add_u32_e32 v3, 0x2cb8, v9
	ds_write2_b32 v3, v56, v57 offset1:1
	v_add_u32_e32 v3, 0x30c0, v9
	ds_write2_b32 v3, v58, v59 offset1:1
	v_add_u32_e32 v3, 0x30c8, v9
	ds_write2_b32 v3, v60, v61 offset1:1
	v_add_u32_e32 v3, 0x34d0, v9
	ds_write2_b32 v3, v62, v63 offset1:1
	v_add_u32_e32 v3, 0x34d8, v9
	ds_write2_b32 v3, v64, v65 offset1:1
	v_add_u32_e32 v3, 0x38e0, v9
	ds_write2_b32 v3, v66, v67 offset1:1
	v_add_u32_e32 v3, 0x38e8, v9
	ds_write2_b32 v3, v68, v69 offset1:1
	v_add_u32_e32 v3, 0x3cf0, v9
	ds_write2_b32 v3, v70, v71 offset1:1
	v_add_u32_e32 v3, 0x3cf8, v9
	ds_write2_b32 v3, v72, v73 offset1:1
	s_waitcnt lgkmcnt(0)
	v_mov_b32_e32 v3, v1
	ds_read2_b32 v[10:11], v8 offset1:65
	v_lshl_add_u64 v[4:5], s[42:43], 0, v[2:3]
	s_waitcnt lgkmcnt(0)
	v_cvt_pk_bf16_f32 v10, v10, v11
	ds_read2_b32 v[12:13], v8 offset0:130 offset1:195
	v_add_u32_e32 v3, 0x400, v8
	s_waitcnt lgkmcnt(0)
	v_cvt_pk_bf16_f32 v11, v12, v13
	ds_read2_b32 v[12:13], v3 offset0:4 offset1:69
	s_waitcnt lgkmcnt(0)
	v_cvt_pk_bf16_f32 v12, v12, v13
	ds_read2_b32 v[14:15], v3 offset0:134 offset1:199
	v_add_u32_e32 v16, s14, v7
	s_waitcnt lgkmcnt(0)
	v_cvt_pk_bf16_f32 v13, v14, v15
	v_mad_i64_i32 v[14:15], s[14:15], v16, s13, 0
	v_lshl_add_u64 v[14:15], v[14:15], 1, v[4:5]
	global_store_dwordx4 v[14:15], v[10:13], off sc0 sc1
	ds_read2_b32 v[10:11], v8 offset0:8 offset1:73
	s_waitcnt lgkmcnt(0)
	v_cvt_pk_bf16_f32 v10, v10, v11
	ds_read2_b32 v[12:13], v8 offset0:138 offset1:203
	s_waitcnt lgkmcnt(0)
	v_cvt_pk_bf16_f32 v11, v12, v13
	ds_read2_b32 v[12:13], v3 offset0:12 offset1:77
	s_waitcnt lgkmcnt(0)
	v_cvt_pk_bf16_f32 v12, v12, v13
	ds_read2_b32 v[14:15], v3 offset0:142 offset1:207
	s_waitcnt lgkmcnt(0)
	v_cvt_pk_bf16_f32 v13, v14, v15
	v_add_u32_e32 v14, 8, v16
	v_mad_i64_i32 v[14:15], s[14:15], v14, s13, 0
	v_lshl_add_u64 v[14:15], v[14:15], 1, v[4:5]
	global_store_dwordx4 v[14:15], v[10:13], off sc0 sc1
	ds_read2_b32 v[10:11], v8 offset0:16 offset1:81
	s_waitcnt lgkmcnt(0)
	v_cvt_pk_bf16_f32 v10, v10, v11
	ds_read2_b32 v[12:13], v8 offset0:146 offset1:211
	s_waitcnt lgkmcnt(0)
	v_cvt_pk_bf16_f32 v11, v12, v13
	ds_read2_b32 v[12:13], v3 offset0:20 offset1:85
	s_waitcnt lgkmcnt(0)
	v_cvt_pk_bf16_f32 v12, v12, v13
	ds_read2_b32 v[14:15], v3 offset0:150 offset1:215
	s_waitcnt lgkmcnt(0)
	v_cvt_pk_bf16_f32 v13, v14, v15
	v_add_u32_e32 v14, 16, v16
	v_mad_i64_i32 v[14:15], s[14:15], v14, s13, 0
	v_lshl_add_u64 v[14:15], v[14:15], 1, v[4:5]
	global_store_dwordx4 v[14:15], v[10:13], off sc0 sc1
	ds_read2_b32 v[10:11], v8 offset0:24 offset1:89
	s_waitcnt lgkmcnt(0)
	v_cvt_pk_bf16_f32 v10, v10, v11
	ds_read2_b32 v[12:13], v8 offset0:154 offset1:219
	s_waitcnt lgkmcnt(0)
	v_cvt_pk_bf16_f32 v11, v12, v13
	ds_read2_b32 v[12:13], v3 offset0:28 offset1:93
	s_waitcnt lgkmcnt(0)
	v_cvt_pk_bf16_f32 v12, v12, v13
	ds_read2_b32 v[14:15], v3 offset0:158 offset1:223
	s_waitcnt lgkmcnt(0)
	v_cvt_pk_bf16_f32 v13, v14, v15
	v_add_u32_e32 v14, 24, v16
	v_mad_i64_i32 v[14:15], s[14:15], v14, s13, 0
	v_lshl_add_u64 v[14:15], v[14:15], 1, v[4:5]
	global_store_dwordx4 v[14:15], v[10:13], off sc0 sc1
	ds_read2_b32 v[10:11], v8 offset0:32 offset1:97
	s_waitcnt lgkmcnt(0)
	v_cvt_pk_bf16_f32 v10, v10, v11
	ds_read2_b32 v[12:13], v8 offset0:162 offset1:227
	s_waitcnt lgkmcnt(0)
	v_cvt_pk_bf16_f32 v11, v12, v13
	ds_read2_b32 v[12:13], v3 offset0:36 offset1:101
	s_waitcnt lgkmcnt(0)
	v_cvt_pk_bf16_f32 v12, v12, v13
	ds_read2_b32 v[14:15], v3 offset0:166 offset1:231
	s_waitcnt lgkmcnt(0)
	v_cvt_pk_bf16_f32 v13, v14, v15
	v_add_u32_e32 v14, 32, v16
	v_mad_i64_i32 v[14:15], s[14:15], v14, s13, 0
	v_lshl_add_u64 v[14:15], v[14:15], 1, v[4:5]
	global_store_dwordx4 v[14:15], v[10:13], off sc0 sc1
	ds_read2_b32 v[10:11], v8 offset0:40 offset1:105
	s_waitcnt lgkmcnt(0)
	v_cvt_pk_bf16_f32 v10, v10, v11
	ds_read2_b32 v[12:13], v8 offset0:170 offset1:235
	s_waitcnt lgkmcnt(0)
	v_cvt_pk_bf16_f32 v11, v12, v13
	ds_read2_b32 v[12:13], v3 offset0:44 offset1:109
	s_waitcnt lgkmcnt(0)
	v_cvt_pk_bf16_f32 v12, v12, v13
	ds_read2_b32 v[14:15], v3 offset0:174 offset1:239
	s_waitcnt lgkmcnt(0)
	v_cvt_pk_bf16_f32 v13, v14, v15
	v_add_u32_e32 v14, 40, v16
	v_mad_i64_i32 v[14:15], s[14:15], v14, s13, 0
	v_lshl_add_u64 v[14:15], v[14:15], 1, v[4:5]
	global_store_dwordx4 v[14:15], v[10:13], off sc0 sc1
	ds_read2_b32 v[10:11], v8 offset0:48 offset1:113
	s_waitcnt lgkmcnt(0)
	v_cvt_pk_bf16_f32 v10, v10, v11
	ds_read2_b32 v[12:13], v8 offset0:178 offset1:243
	s_waitcnt lgkmcnt(0)
	v_cvt_pk_bf16_f32 v11, v12, v13
	ds_read2_b32 v[12:13], v3 offset0:52 offset1:117
	s_waitcnt lgkmcnt(0)
	v_cvt_pk_bf16_f32 v12, v12, v13
	ds_read2_b32 v[14:15], v3 offset0:182 offset1:247
	s_waitcnt lgkmcnt(0)
	v_cvt_pk_bf16_f32 v13, v14, v15
	v_add_u32_e32 v14, 48, v16
	v_mad_i64_i32 v[14:15], s[14:15], v14, s13, 0
	v_lshl_add_u64 v[14:15], v[14:15], 1, v[4:5]
	global_store_dwordx4 v[14:15], v[10:13], off sc0 sc1
	ds_read2_b32 v[10:11], v8 offset0:56 offset1:121
	s_waitcnt lgkmcnt(0)
	v_cvt_pk_bf16_f32 v10, v10, v11
	ds_read2_b32 v[12:13], v8 offset0:186 offset1:251
	s_waitcnt lgkmcnt(0)
	v_cvt_pk_bf16_f32 v11, v12, v13
	ds_read2_b32 v[12:13], v3 offset0:60 offset1:125
	s_waitcnt lgkmcnt(0)
	v_cvt_pk_bf16_f32 v12, v12, v13
	ds_read2_b32 v[14:15], v3 offset0:190 offset1:255
	v_add_u32_e32 v3, 56, v16
	s_waitcnt lgkmcnt(0)
	v_cvt_pk_bf16_f32 v13, v14, v15
	v_mad_i64_i32 v[14:15], s[14:15], v3, s13, 0
	v_lshl_add_u64 v[4:5], v[14:15], 1, v[4:5]
	global_store_dwordx4 v[4:5], v[10:13], off sc0 sc1
	s_waitcnt lgkmcnt(0)
	s_cbranch_scc0 .LBB0_251

.LBB0_327:
	s_and_b64 vcc, exec, s[6:7]
	s_movk_i32 s87, 0xff7d
	s_cbranch_vccnz .LBB0_331
	s_lshr_b32 s6, s97, 5
	s_and_b32 s6, s6, 0x7800000
	v_lshl_or_b32 v156, s22, 8, v154
	s_add_u32 s22, s83, s6
	s_addc_u32 s33, s95, 0
	s_lshl_b32 s6, s82, 8
	s_ashr_i32 s7, s6, 31
	s_lshl_b64 s[6:7], s[6:7], 12
	s_add_u32 s6, s22, s6
	s_addc_u32 s7, s33, s7
	v_ashrrev_i32_e32 v157, 31, v156
	v_lshl_add_u64 v[156:157], v[156:157], 2, s[6:7]
	s_brev_b32 s6, 63
	s_mov_b32 s7, -1
	v_lshl_add_u64 v[156:157], v[156:157], 0, s[6:7]
	v_lshl_add_u64 v[158:159], v[156:157], 0, v[132:133]
	global_store_dwordx4 v[158:159], v[126:129], off sc0 sc1
	global_store_dwordx4 v[158:159], v[106:109], off offset:64 sc0 sc1
	global_store_dwordx4 v[158:159], v[66:69], off offset:512 sc0 sc1
	global_store_dwordx4 v[158:159], v[86:89], off offset:576 sc0 sc1
	s_andn2_b64 vcc, exec, s[26:27]
	v_lshl_add_u64 v[66:67], v[156:157], 0, v[134:135]
	global_store_dwordx4 v[66:67], v[122:125], off sc0 sc1
	global_store_dwordx4 v[66:67], v[98:101], off offset:64 sc0 sc1
	global_store_dwordx4 v[66:67], v[54:57], off offset:512 sc0 sc1
	global_store_dwordx4 v[66:67], v[82:85], off offset:576 sc0 sc1
	s_nop 0
	v_lshl_add_u64 v[54:55], v[156:157], 0, v[136:137]
	global_store_dwordx4 v[54:55], v[118:121], off sc0 sc1
	global_store_dwordx4 v[54:55], v[90:93], off offset:64 sc0 sc1
	global_store_dwordx4 v[54:55], v[46:49], off offset:512 sc0 sc1
	global_store_dwordx4 v[54:55], v[26:29], off offset:576 sc0 sc1
	s_nop 1
	v_lshl_add_u64 v[26:27], v[156:157], 0, v[138:139]
	global_store_dwordx4 v[26:27], v[114:117], off sc0 sc1
	global_store_dwordx4 v[26:27], v[78:81], off offset:64 sc0 sc1
	global_store_dwordx4 v[26:27], v[42:45], off offset:512 sc0 sc1
	global_store_dwordx4 v[26:27], v[18:21], off offset:576 sc0 sc1
	s_nop 1
	v_lshl_add_u64 v[18:19], v[156:157], 0, v[140:141]
	global_store_dwordx4 v[18:19], v[110:113], off sc0 sc1
	global_store_dwordx4 v[18:19], v[70:73], off offset:64 sc0 sc1
	global_store_dwordx4 v[18:19], v[38:41], off offset:512 sc0 sc1
	global_store_dwordx4 v[18:19], v[14:17], off offset:576 sc0 sc1
	s_nop 1
	v_lshl_add_u64 v[14:15], v[156:157], 0, v[142:143]
	global_store_dwordx4 v[14:15], v[102:105], off sc0 sc1
	global_store_dwordx4 v[14:15], v[62:65], off offset:64 sc0 sc1
	global_store_dwordx4 v[14:15], v[34:37], off offset:512 sc0 sc1
	global_store_dwordx4 v[14:15], v[10:13], off offset:576 sc0 sc1
	s_nop 1
	v_lshl_add_u64 v[10:11], v[156:157], 0, v[144:145]
	global_store_dwordx4 v[10:11], v[94:97], off sc0 sc1
	global_store_dwordx4 v[10:11], v[58:61], off offset:64 sc0 sc1
	global_store_dwordx4 v[10:11], v[30:33], off offset:512 sc0 sc1
	global_store_dwordx4 v[10:11], v[6:9], off offset:576 sc0 sc1
	s_nop 1
	v_lshl_add_u64 v[6:7], v[156:157], 0, v[146:147]
	global_store_dwordx4 v[6:7], v[74:77], off sc0 sc1
	global_store_dwordx4 v[6:7], v[50:53], off offset:64 sc0 sc1
	global_store_dwordx4 v[6:7], v[22:25], off offset:512 sc0 sc1
	global_store_dwordx4 v[6:7], v[2:5], off offset:576 sc0 sc1
	s_cbranch_vccnz .LBB0_330
	s_barrier

.LBB0_382:
	v_lshl_add_u32 v0, v196, 3, 0
	ds_read_b64 v[206:207], v0 offset:8192
	s_lshl_b64 s[8:9], s[24:25], 12
	s_add_u32 s20, s20, s8
	s_addc_u32 s21, s21, s9
	s_sub_u32 s2, 0, s26
	s_subb_u32 s8, 0, s27
	s_waitcnt lgkmcnt(0)
	v_sub_f32_e32 v143, v143, v206
	v_sub_f32_e32 v142, v142, v206
	v_sub_f32_e32 v145, v145, v206
	v_sub_f32_e32 v144, v144, v206
	s_add_u32 s10, s20, s2
	v_lshlrev_b64 v[196:197], 10, v[196:197]
	v_pk_mul_f32 v[144:145], v[206:207], v[144:145] op_sel:[1,0]
	v_pk_mul_f32 v[142:143], v[206:207], v[142:143] op_sel:[1,0]
	s_addc_u32 s11, s21, s8
	v_lshl_add_u64 v[196:197], v[196:197], 0, v[180:181]
	s_waitcnt vmcnt(6)
	v_pk_fma_f32 v[142:143], v[158:159], v[142:143], v[162:163]
	v_pk_fma_f32 v[144:145], v[160:161], v[144:145], v[164:165]
	v_cmp_eq_u32_e64 s[8:9], 0, v208
	s_mov_b64 s[22:23], -1
	s_and_b64 vcc, exec, s[4:5]
	v_cndmask_b32_e64 v145, v250, v145, s[8:9]
	v_cndmask_b32_e64 v144, v250, v144, s[8:9]
	v_cndmask_b32_e64 v143, v250, v143, s[8:9]
	v_cndmask_b32_e64 v142, v250, v142, s[8:9]
	v_lshl_add_u64 v[208:209], v[196:197], 2, s[20:21]
	s_cbranch_vccnz .LBB0_384
	s_mov_b64 s[22:23], 0
	global_store_dwordx4 v[208:209], v[142:145], off sc0 sc1

.LBB0_528:
	global_store_dwordx4 v[194:195], v[138:141], off sc0 sc1
	v_lshl_add_u64 v[144:145], v[142:143], 1, s[10:11]
	s_cbranch_execnz .LBB0_390

.LBB0_530:
	global_store_dwordx4 v[192:193], v[134:137], off sc0 sc1
	v_lshl_add_u64 v[140:141], v[138:139], 1, s[10:11]
	s_cbranch_execnz .LBB0_394

.LBB0_532:
	global_store_dwordx4 v[190:191], v[130:133], off sc0 sc1
	v_lshl_add_u64 v[136:137], v[134:135], 1, s[10:11]
	s_cbranch_execnz .LBB0_398

.LBB0_534:
	global_store_dwordx4 v[188:189], v[126:129], off sc0 sc1
	v_lshl_add_u64 v[132:133], v[130:131], 1, s[10:11]
	s_cbranch_execnz .LBB0_402

.LBB0_536:
	global_store_dwordx4 v[186:187], v[122:125], off sc0 sc1
	v_lshl_add_u64 v[128:129], v[126:127], 1, s[10:11]
	s_cbranch_execnz .LBB0_406

.LBB0_538:
	global_store_dwordx4 v[184:185], v[118:121], off sc0 sc1
	v_lshl_add_u64 v[124:125], v[122:123], 1, s[10:11]
	s_cbranch_execnz .LBB0_410

.LBB0_540:
	global_store_dwordx4 v[158:159], v[114:117], off sc0 sc1
	v_lshl_add_u64 v[120:121], v[118:119], 1, s[10:11]
	s_cbranch_execnz .LBB0_414

.LBB0_542:
	global_store_dwordx4 v[208:209], v[110:113], off offset:64 sc0 sc1
	s_cbranch_execnz .LBB0_418

.LBB0_544:
	global_store_dwordx4 v[194:195], v[106:109], off offset:64 sc0 sc1
	s_cbranch_execnz .LBB0_422

.LBB0_546:
	global_store_dwordx4 v[192:193], v[102:105], off offset:64 sc0 sc1
	s_cbranch_execnz .LBB0_426

.LBB0_548:
	global_store_dwordx4 v[190:191], v[98:101], off offset:64 sc0 sc1
	s_cbranch_execnz .LBB0_430

.LBB0_550:
	global_store_dwordx4 v[188:189], v[94:97], off offset:64 sc0 sc1
	s_cbranch_execnz .LBB0_434

.LBB0_552:
	global_store_dwordx4 v[186:187], v[90:93], off offset:64 sc0 sc1
	s_cbranch_execnz .LBB0_438

.LBB0_554:
	global_store_dwordx4 v[184:185], v[78:81], off offset:64 sc0 sc1
	s_cbranch_execnz .LBB0_442

.LBB0_556:
	global_store_dwordx4 v[158:159], v[74:77], off offset:64 sc0 sc1
	s_cbranch_execnz .LBB0_446

.LBB0_558:
	global_store_dwordx4 v[208:209], v[70:73], off offset:512 sc0 sc1
	s_cbranch_execnz .LBB0_450

.LBB0_560:
	global_store_dwordx4 v[194:195], v[66:69], off offset:512 sc0 sc1
	s_cbranch_execnz .LBB0_454

.LBB0_562:
	global_store_dwordx4 v[192:193], v[62:65], off offset:512 sc0 sc1
	s_cbranch_execnz .LBB0_458

.LBB0_564:
	global_store_dwordx4 v[190:191], v[58:61], off offset:512 sc0 sc1
	s_cbranch_execnz .LBB0_462

.LBB0_566:
	global_store_dwordx4 v[188:189], v[54:57], off offset:512 sc0 sc1
	s_cbranch_execnz .LBB0_466

.LBB0_568:
	global_store_dwordx4 v[186:187], v[50:53], off offset:512 sc0 sc1
	s_cbranch_execnz .LBB0_470

.LBB0_570:
	global_store_dwordx4 v[184:185], v[46:49], off offset:512 sc0 sc1
	s_cbranch_execnz .LBB0_474

.LBB0_572:
	global_store_dwordx4 v[158:159], v[42:45], off offset:512 sc0 sc1
	s_cbranch_execnz .LBB0_478

.LBB0_574:
	global_store_dwordx4 v[208:209], v[38:41], off offset:576 sc0 sc1
	s_cbranch_execnz .LBB0_482

.LBB0_576:
	global_store_dwordx4 v[194:195], v[30:33], off offset:576 sc0 sc1
	s_cbranch_execnz .LBB0_486

.LBB0_578:
	global_store_dwordx4 v[192:193], v[30:33], off offset:576 sc0 sc1
	s_cbranch_execnz .LBB0_490

.LBB0_580:
	global_store_dwordx4 v[190:191], v[26:29], off offset:576 sc0 sc1
	s_cbranch_execnz .LBB0_494

.LBB0_582:
	global_store_dwordx4 v[188:189], v[22:25], off offset:576 sc0 sc1
	s_cbranch_execnz .LBB0_498

.LBB0_584:
	global_store_dwordx4 v[186:187], v[18:21], off offset:576 sc0 sc1
	s_cbranch_execnz .LBB0_502

.LBB0_586:
	global_store_dwordx4 v[184:185], v[14:17], off offset:576 sc0 sc1
	s_cbranch_execnz .LBB0_506

.LBB0_588:
	global_store_dwordx4 v[158:159], v[2:5], off offset:576 sc0 sc1
	s_cbranch_execnz .LBB0_510

.LBB0_713:
	s_cmpk_lt_i32 s30, 0x400
	s_cselect_b64 vcc, -1, 0
	v_cndmask_b32_e32 v132, 1.0, v251, vcc
	v_or_b32_e32 v155, s2, v148
	v_pk_mul_f32 v[126:127], v[132:133], v[126:127] op_sel_hi:[0,1]
	v_or_b32_e32 v130, s30, v140
	v_pk_mul_f32 v[156:157], v[132:133], v[124:125] op_sel_hi:[0,1]
	v_pk_mul_f32 v[124:125], v[132:133], v[122:123] op_sel_hi:[0,1]
	v_cvt_pk_bf16_f32 v122, v126, v127
	v_mad_i64_i32 v[126:127], s[36:37], v155, s52, 0
	v_ashrrev_i32_e32 v131, 31, v130
	v_pk_mul_f32 v[128:129], v[132:133], v[128:129] op_sel_hi:[0,1]
	v_lshl_add_u64 v[126:127], v[126:127], 1, s[18:19]
	v_cvt_pk_bf16_f32 v123, v128, v129
	v_lshl_add_u64 v[128:129], v[130:131], 1, v[126:127]
	s_and_b64 vcc, exec, s[10:11]
	v_cvt_pk_bf16_f32 v124, v124, v125
	v_cvt_pk_bf16_f32 v125, v156, v157
	global_store_dwordx4 v[128:129], v[122:125], off sc0 sc1
	s_cbranch_vccnz .LBB0_715
	s_nop 0
	v_and_b32_e32 v123, 64, v249
	v_xor_b32_e32 v122, 32, v249
	v_add_u32_e32 v123, 64, v123
	v_cmp_lt_i32_e32 vcc, v122, v123
	s_nop 1
	v_cndmask_b32_e32 v122, v249, v122, vcc
	v_lshlrev_b32_e32 v122, 2, v122
	ds_bpermute_b32 v128, v122, v118
	ds_bpermute_b32 v168, v122, v114
	ds_bpermute_b32 v129, v122, v119
	ds_bpermute_b32 v169, v122, v115
	ds_bpermute_b32 v133, v122, v120
	ds_bpermute_b32 v172, v122, v116
	ds_bpermute_b32 v173, v122, v121
	ds_bpermute_b32 v174, v122, v117
	v_mov_b32_e32 v122, s13
	v_cndmask_b32_e64 v122, v150, v122, s[6:7]
	v_lshl_or_b32 v164, v122, 7, v154
	global_load_dwordx4 v[122:125], v164, s[14:15] offset:48
	global_load_dwordx4 v[156:159], v164, s[14:15] offset:32
	global_load_dwordx4 v[160:163], v164, s[14:15] offset:16
	s_nop 0
	global_load_dwordx4 v[164:167], v164, s[14:15]
	s_waitcnt lgkmcnt(0)
	v_pk_mul_f32 v[128:129], v[142:143], v[128:129]
	v_mul_f32_e32 v133, v142, v133
	s_waitcnt vmcnt(0)
	v_mul_f32_e32 v116, v116, v122
	v_mul_f32_e32 v122, v142, v172
	v_mul_f32_e32 v120, v120, v160
	v_mov_b32_e32 v170, v164
	v_mov_b32_e32 v171, v166
	v_mov_b32_e32 v166, v165
	v_mul_f32_e32 v165, v142, v173
	v_mov_b32_e32 v164, v121
	v_pk_mul_f32 v[162:163], v[164:165], v[162:163]
	v_pk_mul_f32 v[128:129], v[128:129], v[166:167]
	v_mul_f32_e32 v160, v133, v161
	v_mov_b32_e32 v121, v162
	v_mov_b32_e32 v161, v163
	v_pk_fma_f32 v[118:119], v[118:119], v[170:171], v[128:129]
	v_pk_add_f32 v[120:121], v[120:121], v[160:161]
	v_mov_b32_e32 v129, v158
	v_pk_mul_f32 v[160:161], v[142:143], v[168:169]
	v_mov_b32_e32 v158, v157
	v_mov_b32_e32 v128, v156
	v_pk_mul_f32 v[156:157], v[160:161], v[158:159]
	v_mul_f32_e32 v159, v142, v174
	v_mov_b32_e32 v158, v117
	v_pk_mul_f32 v[124:125], v[158:159], v[124:125]
	v_mul_f32_e32 v122, v122, v123
	v_mov_b32_e32 v117, v124
	v_mov_b32_e32 v123, v125
	v_pk_fma_f32 v[114:115], v[114:115], v[128:129], v[156:157]
	v_pk_add_f32 v[116:117], v[116:117], v[122:123]
.LBB0_715:
	v_mov_b32_e32 v133, v132
	v_or_b32_e32 v128, 16, v155
	v_mov_b32_e32 v122, v132
	v_mov_b32_e32 v123, v132
	v_pk_mul_f32 v[118:119], v[132:133], v[118:119]
	v_pk_mul_f32 v[124:125], v[122:123], v[116:117]
	v_pk_mul_f32 v[116:117], v[132:133], v[114:115]
	v_cvt_pk_bf16_f32 v114, v118, v119
	v_mad_i64_i32 v[118:119], s[36:37], v128, s52, 0
	v_pk_mul_f32 v[120:121], v[122:123], v[120:121]
	v_lshl_add_u64 v[118:119], v[118:119], 1, s[18:19]
	v_cvt_pk_bf16_f32 v115, v120, v121
	v_lshl_add_u64 v[120:121], v[130:131], 1, v[118:119]
	s_and_b64 vcc, exec, s[10:11]
	v_cvt_pk_bf16_f32 v116, v116, v117
	v_cvt_pk_bf16_f32 v117, v124, v125
	global_store_dwordx4 v[120:121], v[114:117], off sc0 sc1
	s_cbranch_vccnz .LBB0_717
	s_nop 0
	v_and_b32_e32 v115, 64, v249
	v_xor_b32_e32 v114, 32, v249
	v_add_u32_e32 v115, 64, v115
	v_cmp_lt_i32_e32 vcc, v114, v115
	s_nop 1
	v_cndmask_b32_e32 v114, v249, v114, vcc
	v_lshlrev_b32_e32 v114, 2, v114
	ds_bpermute_b32 v120, v114, v110
	ds_bpermute_b32 v124, v114, v106
	ds_bpermute_b32 v121, v114, v111
	ds_bpermute_b32 v125, v114, v107
	ds_bpermute_b32 v168, v114, v112
	ds_bpermute_b32 v169, v114, v108
	ds_bpermute_b32 v170, v114, v113
	ds_bpermute_b32 v171, v114, v109
	v_mov_b32_e32 v114, s13
	v_cndmask_b32_e64 v114, v151, v114, s[6:7]
	v_lshl_or_b32 v128, v114, 7, v154
	global_load_dwordx4 v[114:117], v128, s[14:15] offset:48
	global_load_dwordx4 v[156:159], v128, s[14:15] offset:32
	global_load_dwordx4 v[160:163], v128, s[14:15] offset:16
	global_load_dwordx4 v[164:167], v128, s[14:15]
	s_waitcnt lgkmcnt(0)
	v_pk_mul_f32 v[120:121], v[142:143], v[120:121]
	v_pk_mul_f32 v[124:125], v[142:143], v[124:125]
	s_waitcnt vmcnt(0)
	v_mul_f32_e32 v108, v108, v114
	v_mul_f32_e32 v114, v142, v169
	v_mul_f32_e32 v112, v112, v160
	v_mov_b32_e32 v129, v166
	v_mov_b32_e32 v166, v165
	v_mov_b32_e32 v128, v164
	v_pk_mul_f32 v[120:121], v[120:121], v[166:167]
	v_mul_f32_e32 v165, v142, v170
	v_mov_b32_e32 v164, v113
	v_pk_fma_f32 v[110:111], v[110:111], v[128:129], v[120:121]
	v_mul_f32_e32 v129, v142, v171
	v_mov_b32_e32 v128, v109
	v_mul_f32_e32 v160, v142, v168
	v_pk_mul_f32 v[162:163], v[164:165], v[162:163]
	v_mov_b32_e32 v121, v158
	v_mov_b32_e32 v158, v157
	v_pk_mul_f32 v[116:117], v[128:129], v[116:117]
	v_mul_f32_e32 v160, v160, v161
	v_mov_b32_e32 v113, v162
	v_mov_b32_e32 v161, v163
	v_mov_b32_e32 v120, v156
	v_pk_mul_f32 v[124:125], v[124:125], v[158:159]
	v_mul_f32_e32 v114, v114, v115
	v_mov_b32_e32 v109, v116
	v_mov_b32_e32 v115, v117
	v_pk_add_f32 v[112:113], v[112:113], v[160:161]
	v_pk_fma_f32 v[106:107], v[106:107], v[120:121], v[124:125]
	v_pk_add_f32 v[108:109], v[108:109], v[114:115]
.LBB0_717:
	s_nop 0
	v_or_b32_e32 v116, 32, v155
	v_pk_mul_f32 v[110:111], v[132:133], v[110:111]
	v_pk_mul_f32 v[114:115], v[122:123], v[108:109]
	v_pk_mul_f32 v[108:109], v[132:133], v[106:107]
	v_cvt_pk_bf16_f32 v106, v110, v111
	v_mad_i64_i32 v[110:111], s[36:37], v116, s52, 0
	v_pk_mul_f32 v[112:113], v[122:123], v[112:113]
	v_lshl_add_u64 v[110:111], v[110:111], 1, s[18:19]
	v_cvt_pk_bf16_f32 v107, v112, v113
	v_lshl_add_u64 v[112:113], v[130:131], 1, v[110:111]
	s_and_b64 vcc, exec, s[10:11]
	v_cvt_pk_bf16_f32 v108, v108, v109
	v_cvt_pk_bf16_f32 v109, v114, v115
	global_store_dwordx4 v[112:113], v[106:109], off sc0 sc1
	s_cbranch_vccnz .LBB0_719
	s_nop 0
	v_and_b32_e32 v107, 64, v249
	v_xor_b32_e32 v106, 32, v249
	v_add_u32_e32 v107, 64, v107
	v_cmp_lt_i32_e32 vcc, v106, v107
	s_nop 1
	v_cndmask_b32_e32 v106, v249, v106, vcc
	v_lshlrev_b32_e32 v106, 2, v106
	ds_bpermute_b32 v116, v106, v102
	ds_bpermute_b32 v124, v106, v98
	ds_bpermute_b32 v117, v106, v103
	ds_bpermute_b32 v125, v106, v99
	ds_bpermute_b32 v160, v106, v104
	ds_bpermute_b32 v161, v106, v100
	ds_bpermute_b32 v162, v106, v105
	ds_bpermute_b32 v163, v106, v101
	v_mov_b32_e32 v106, s13
	v_cndmask_b32_e64 v106, v152, v106, s[6:7]
	v_lshl_or_b32 v128, v106, 7, v154
	global_load_dwordx4 v[106:109], v128, s[14:15] offset:48
	global_load_dwordx4 v[112:115], v128, s[14:15] offset:32
	global_load_dwordx4 v[120:123], v128, s[14:15] offset:16
	global_load_dwordx4 v[156:159], v128, s[14:15]
	s_waitcnt lgkmcnt(0)
	v_pk_mul_f32 v[116:117], v[142:143], v[116:117]
	s_waitcnt vmcnt(0)
	v_mul_f32_e32 v100, v100, v106
	v_mul_f32_e32 v106, v142, v161
	v_mul_f32_e32 v104, v104, v120
	v_mov_b32_e32 v128, v156
	v_mov_b32_e32 v129, v158
	v_mov_b32_e32 v158, v157
	v_mul_f32_e32 v157, v142, v162
	v_mov_b32_e32 v156, v105
	v_mul_f32_e32 v120, v142, v160
	v_pk_mul_f32 v[122:123], v[156:157], v[122:123]
	v_pk_mul_f32 v[116:117], v[116:117], v[158:159]
	v_mul_f32_e32 v120, v120, v121
	v_mov_b32_e32 v105, v122
	v_mov_b32_e32 v121, v123
	v_pk_fma_f32 v[102:103], v[102:103], v[128:129], v[116:117]
	v_pk_add_f32 v[104:105], v[104:105], v[120:121]
	v_mov_b32_e32 v117, v114
	v_pk_mul_f32 v[120:121], v[142:143], v[124:125]
	v_mov_b32_e32 v114, v113
	v_mov_b32_e32 v116, v112
	v_pk_mul_f32 v[112:113], v[120:121], v[114:115]
	v_mul_f32_e32 v115, v142, v163
	v_mov_b32_e32 v114, v101
	v_pk_mul_f32 v[108:109], v[114:115], v[108:109]
	v_mul_f32_e32 v106, v106, v107
	v_mov_b32_e32 v101, v108
	v_mov_b32_e32 v107, v109
	v_pk_fma_f32 v[98:99], v[98:99], v[116:117], v[112:113]
	v_pk_add_f32 v[100:101], v[100:101], v[106:107]
.LBB0_719:
	v_or_b32_e32 v112, 48, v155
	v_mov_b32_e32 v106, v132
	v_mov_b32_e32 v107, v132
	v_pk_mul_f32 v[102:103], v[132:133], v[102:103]
	v_pk_mul_f32 v[108:109], v[106:107], v[100:101]
	v_pk_mul_f32 v[100:101], v[132:133], v[98:99]
	v_cvt_pk_bf16_f32 v98, v102, v103
	v_mad_i64_i32 v[102:103], s[36:37], v112, s52, 0
	v_pk_mul_f32 v[104:105], v[106:107], v[104:105]
	v_lshl_add_u64 v[102:103], v[102:103], 1, s[18:19]
	v_cvt_pk_bf16_f32 v99, v104, v105
	v_cvt_pk_bf16_f32 v100, v100, v101
	v_cvt_pk_bf16_f32 v101, v108, v109
	v_lshl_add_u64 v[104:105], v[130:131], 1, v[102:103]
	v_add_u32_e32 v108, 0x80, v155
	global_store_dwordx4 v[104:105], v[98:101], off sc0 sc1
	v_bfe_u32 v105, v108, 6, 5
	s_and_b64 vcc, exec, s[10:11]
	v_cndmask_b32_e64 v98, v148, v105, s[6:7]
	v_lshl_or_b32 v104, v98, 7, v154
	s_cbranch_vccnz .LBB0_721
	v_and_b32_e32 v99, 64, v249
	v_xor_b32_e32 v98, 32, v249
	v_add_u32_e32 v99, 64, v99
	v_cmp_lt_i32_e32 vcc, v98, v99
	s_nop 1
	v_cndmask_b32_e32 v98, v249, v98, vcc
	v_lshlrev_b32_e32 v98, 2, v98
	ds_bpermute_b32 v116, v98, v94
	ds_bpermute_b32 v124, v98, v90
	ds_bpermute_b32 v117, v98, v95
	ds_bpermute_b32 v125, v98, v91
	ds_bpermute_b32 v109, v98, v96
	ds_bpermute_b32 v160, v98, v92
	ds_bpermute_b32 v161, v98, v97
	ds_bpermute_b32 v162, v98, v93
	global_load_dwordx4 v[98:101], v104, s[14:15] offset:48
	global_load_dwordx4 v[112:115], v104, s[14:15] offset:32
	global_load_dwordx4 v[120:123], v104, s[14:15] offset:16
	global_load_dwordx4 v[156:159], v104, s[14:15]
	s_waitcnt lgkmcnt(0)
	v_pk_mul_f32 v[116:117], v[142:143], v[116:117]
	v_mul_f32_e32 v109, v142, v109
	s_waitcnt vmcnt(0)
	v_mul_f32_e32 v92, v92, v98
	v_mul_f32_e32 v98, v142, v160
	v_mul_f32_e32 v96, v96, v120
	v_mov_b32_e32 v128, v156
	v_mov_b32_e32 v129, v158
	v_mov_b32_e32 v158, v157
	v_mul_f32_e32 v157, v142, v161
	v_mov_b32_e32 v156, v97
	v_pk_mul_f32 v[122:123], v[156:157], v[122:123]
	v_pk_mul_f32 v[116:117], v[116:117], v[158:159]
	v_mul_f32_e32 v120, v109, v121
	v_mov_b32_e32 v97, v122
	v_mov_b32_e32 v121, v123
	v_pk_fma_f32 v[94:95], v[94:95], v[128:129], v[116:117]
	v_pk_add_f32 v[96:97], v[96:97], v[120:121]
	v_mov_b32_e32 v117, v114
	v_pk_mul_f32 v[120:121], v[142:143], v[124:125]
	v_mov_b32_e32 v114, v113
	v_mov_b32_e32 v116, v112
	v_pk_mul_f32 v[112:113], v[120:121], v[114:115]
	v_mul_f32_e32 v115, v142, v162
	v_mov_b32_e32 v114, v93
	v_pk_mul_f32 v[100:101], v[114:115], v[100:101]
	v_mul_f32_e32 v98, v98, v99
	v_mov_b32_e32 v93, v100
	v_mov_b32_e32 v99, v101
	v_pk_fma_f32 v[90:91], v[90:91], v[116:117], v[112:113]
	v_pk_add_f32 v[92:93], v[92:93], v[98:99]
.LBB0_721:
	v_pk_mul_f32 v[94:95], v[132:133], v[94:95]
	v_pk_mul_f32 v[98:99], v[106:107], v[92:93]
	v_pk_mul_f32 v[92:93], v[132:133], v[90:91]
	v_cvt_pk_bf16_f32 v90, v94, v95
	v_mad_i64_i32 v[94:95], s[36:37], v108, s52, 0
	v_pk_mul_f32 v[96:97], v[106:107], v[96:97]
	v_lshl_add_u64 v[94:95], v[94:95], 1, s[18:19]
	v_cvt_pk_bf16_f32 v91, v96, v97
	v_lshl_add_u64 v[96:97], v[130:131], 1, v[94:95]
	v_cvt_pk_bf16_f32 v92, v92, v93
	v_cvt_pk_bf16_f32 v93, v98, v99
	global_store_dwordx4 v[96:97], v[90:93], off sc0 sc1
	s_and_b64 vcc, exec, s[10:11]
	s_nop 0
	v_cndmask_b32_e64 v90, v150, v105, s[6:7]
	v_lshl_or_b32 v96, v90, 7, v154
	s_cbranch_vccnz .LBB0_723
	v_and_b32_e32 v91, 64, v249
	v_xor_b32_e32 v90, 32, v249
	v_add_u32_e32 v91, 64, v91
	v_cmp_lt_i32_e32 vcc, v90, v91
	s_nop 1
	v_cndmask_b32_e32 v90, v249, v90, vcc
	v_lshlrev_b32_e32 v90, 2, v90
	ds_bpermute_b32 v116, v90, v86
	ds_bpermute_b32 v120, v90, v82
	ds_bpermute_b32 v117, v90, v87
	ds_bpermute_b32 v121, v90, v83
	ds_bpermute_b32 v97, v90, v88
	ds_bpermute_b32 v124, v90, v84
	ds_bpermute_b32 v125, v90, v89
	ds_bpermute_b32 v128, v90, v85
	global_load_dwordx4 v[90:93], v96, s[14:15] offset:48
	global_load_dwordx4 v[98:101], v96, s[14:15] offset:32
	global_load_dwordx4 v[106:109], v96, s[14:15] offset:16
	global_load_dwordx4 v[112:115], v96, s[14:15]
	s_waitcnt lgkmcnt(0)
	v_pk_mul_f32 v[116:117], v[142:143], v[116:117]
	v_mul_f32_e32 v97, v142, v97
	s_waitcnt vmcnt(0)
	v_mul_f32_e32 v84, v84, v90
	v_mul_f32_e32 v90, v142, v124
	v_mul_f32_e32 v88, v88, v106
	v_mov_b32_e32 v123, v114
	v_mov_b32_e32 v114, v113
	v_mov_b32_e32 v122, v112
	v_pk_mul_f32 v[112:113], v[116:117], v[114:115]
	v_mul_f32_e32 v115, v142, v125
	v_mov_b32_e32 v114, v89
	v_pk_mul_f32 v[108:109], v[114:115], v[108:109]
	v_mul_f32_e32 v106, v97, v107
	v_mov_b32_e32 v89, v108
	v_mov_b32_e32 v107, v109
	v_pk_add_f32 v[88:89], v[88:89], v[106:107]
	v_mov_b32_e32 v107, v100
	v_pk_mul_f32 v[108:109], v[142:143], v[120:121]
	v_mov_b32_e32 v100, v99
	v_mov_b32_e32 v106, v98
	v_pk_mul_f32 v[98:99], v[108:109], v[100:101]
	v_mul_f32_e32 v101, v142, v128
	v_mov_b32_e32 v100, v85
	v_pk_mul_f32 v[92:93], v[100:101], v[92:93]
	v_mul_f32_e32 v90, v90, v91
	v_mov_b32_e32 v85, v92
	v_mov_b32_e32 v91, v93
	v_pk_fma_f32 v[86:87], v[86:87], v[122:123], v[112:113]
	v_pk_fma_f32 v[82:83], v[82:83], v[106:107], v[98:99]
	v_pk_add_f32 v[84:85], v[84:85], v[90:91]
.LBB0_723:
	v_add_u32_e32 v97, 0x90, v155
	v_mov_b32_e32 v90, v132
	v_mov_b32_e32 v91, v132
	v_pk_mul_f32 v[86:87], v[132:133], v[86:87]
	v_pk_mul_f32 v[92:93], v[90:91], v[84:85]
	v_pk_mul_f32 v[84:85], v[132:133], v[82:83]
	v_cvt_pk_bf16_f32 v82, v86, v87
	v_mad_i64_i32 v[86:87], s[36:37], v97, s52, 0
	v_pk_mul_f32 v[88:89], v[90:91], v[88:89]
	v_lshl_add_u64 v[86:87], v[86:87], 1, s[18:19]
	v_cvt_pk_bf16_f32 v83, v88, v89
	v_lshl_add_u64 v[88:89], v[130:131], 1, v[86:87]
	v_cvt_pk_bf16_f32 v84, v84, v85
	v_cvt_pk_bf16_f32 v85, v92, v93
	global_store_dwordx4 v[88:89], v[82:85], off sc0 sc1
	s_and_b64 vcc, exec, s[10:11]
	s_nop 0
	v_cndmask_b32_e64 v82, v151, v105, s[6:7]
	v_lshl_or_b32 v88, v82, 7, v154
	s_cbranch_vccnz .LBB0_725
	v_and_b32_e32 v83, 64, v249
	v_xor_b32_e32 v82, 32, v249
	v_add_u32_e32 v83, 64, v83
	v_cmp_lt_i32_e32 vcc, v82, v83
	s_nop 1
	v_cndmask_b32_e32 v82, v249, v82, vcc
	v_lshlrev_b32_e32 v82, 2, v82
	ds_bpermute_b32 v92, v82, v78
	ds_bpermute_b32 v116, v82, v74
	ds_bpermute_b32 v93, v82, v79
	ds_bpermute_b32 v117, v82, v75
	ds_bpermute_b32 v89, v82, v80
	ds_bpermute_b32 v97, v82, v76
	ds_bpermute_b32 v122, v82, v81
	ds_bpermute_b32 v123, v82, v77
	global_load_dwordx4 v[82:85], v88, s[14:15] offset:48
	global_load_dwordx4 v[98:101], v88, s[14:15] offset:32
	global_load_dwordx4 v[106:109], v88, s[14:15] offset:16
	global_load_dwordx4 v[112:115], v88, s[14:15]
	s_waitcnt lgkmcnt(0)
	v_pk_mul_f32 v[92:93], v[142:143], v[92:93]
	v_mul_f32_e32 v89, v142, v89
	s_waitcnt vmcnt(0)
	v_mul_f32_e32 v76, v76, v82
	v_mul_f32_e32 v82, v142, v97
	v_mul_f32_e32 v80, v80, v106
	v_mov_b32_e32 v120, v112
	v_mov_b32_e32 v121, v114
	v_mov_b32_e32 v114, v113
	v_mul_f32_e32 v113, v142, v122
	v_mov_b32_e32 v112, v81
	v_pk_mul_f32 v[108:109], v[112:113], v[108:109]
	v_pk_mul_f32 v[92:93], v[92:93], v[114:115]
	v_mul_f32_e32 v106, v89, v107
	v_mov_b32_e32 v81, v108
	v_mov_b32_e32 v107, v109
	v_pk_fma_f32 v[78:79], v[78:79], v[120:121], v[92:93]
	v_pk_add_f32 v[80:81], v[80:81], v[106:107]
	v_mov_b32_e32 v93, v100
	v_pk_mul_f32 v[106:107], v[142:143], v[116:117]
	v_mov_b32_e32 v100, v99
	v_mov_b32_e32 v92, v98
	v_pk_mul_f32 v[98:99], v[106:107], v[100:101]
	v_mul_f32_e32 v101, v142, v123
	v_mov_b32_e32 v100, v77
	v_pk_mul_f32 v[84:85], v[100:101], v[84:85]
	v_mul_f32_e32 v82, v82, v83
	v_mov_b32_e32 v77, v84
	v_mov_b32_e32 v83, v85
	v_pk_fma_f32 v[74:75], v[74:75], v[92:93], v[98:99]
	v_pk_add_f32 v[76:77], v[76:77], v[82:83]
.LBB0_725:
	v_add_u32_e32 v84, 0xa0, v155
	v_pk_mul_f32 v[78:79], v[132:133], v[78:79]
	v_pk_mul_f32 v[82:83], v[90:91], v[76:77]
	v_pk_mul_f32 v[76:77], v[132:133], v[74:75]
	v_cvt_pk_bf16_f32 v74, v78, v79
	v_mad_i64_i32 v[78:79], s[36:37], v84, s52, 0
	v_pk_mul_f32 v[80:81], v[90:91], v[80:81]
	v_lshl_add_u64 v[78:79], v[78:79], 1, s[18:19]
	v_cvt_pk_bf16_f32 v75, v80, v81
	v_lshl_add_u64 v[80:81], v[130:131], 1, v[78:79]
	v_cvt_pk_bf16_f32 v76, v76, v77
	v_cvt_pk_bf16_f32 v77, v82, v83
	global_store_dwordx4 v[80:81], v[74:77], off sc0 sc1
	s_and_b64 vcc, exec, s[10:11]
	s_nop 0
	v_cndmask_b32_e64 v74, v152, v105, s[6:7]
	v_lshl_or_b32 v80, v74, 7, v154
	s_cbranch_vccnz .LBB0_727
	v_and_b32_e32 v75, 64, v249
	v_xor_b32_e32 v74, 32, v249
	v_add_u32_e32 v75, 64, v75
	v_cmp_lt_i32_e32 vcc, v74, v75
	s_nop 1
	v_cndmask_b32_e32 v74, v249, v74, vcc
	v_lshlrev_b32_e32 v74, 2, v74
	ds_bpermute_b32 v106, v74, v70
	ds_bpermute_b32 v108, v74, v66
	ds_bpermute_b32 v107, v74, v71
	ds_bpermute_b32 v109, v74, v67
	ds_bpermute_b32 v81, v74, v72
	ds_bpermute_b32 v89, v74, v68
	ds_bpermute_b32 v97, v74, v73
	ds_bpermute_b32 v105, v74, v69
	global_load_dwordx4 v[74:77], v80, s[14:15] offset:48
	global_load_dwordx4 v[82:85], v80, s[14:15] offset:32
	global_load_dwordx4 v[90:93], v80, s[14:15] offset:16
	global_load_dwordx4 v[98:101], v80, s[14:15]
	s_waitcnt lgkmcnt(0)
	v_pk_mul_f32 v[106:107], v[142:143], v[106:107]
	v_mul_f32_e32 v81, v142, v81
	s_waitcnt vmcnt(0)
	v_mul_f32_e32 v68, v68, v74
	v_mul_f32_e32 v74, v142, v89
	v_mul_f32_e32 v72, v72, v90
	v_mov_b32_e32 v113, v100
	v_mov_b32_e32 v100, v99
	v_mov_b32_e32 v112, v98
	v_pk_mul_f32 v[98:99], v[106:107], v[100:101]
	v_mul_f32_e32 v101, v142, v97
	v_mov_b32_e32 v100, v73
	v_pk_mul_f32 v[92:93], v[100:101], v[92:93]
	v_mul_f32_e32 v90, v81, v91
	v_mov_b32_e32 v73, v92
	v_mov_b32_e32 v91, v93
	v_pk_add_f32 v[72:73], v[72:73], v[90:91]
	v_mov_b32_e32 v91, v84
	v_pk_mul_f32 v[92:93], v[142:143], v[108:109]
	v_mov_b32_e32 v84, v83
	v_mov_b32_e32 v90, v82
	v_pk_mul_f32 v[82:83], v[92:93], v[84:85]
	v_mul_f32_e32 v85, v142, v105
	v_mov_b32_e32 v84, v69
	v_pk_mul_f32 v[76:77], v[84:85], v[76:77]
	v_mul_f32_e32 v74, v74, v75
	v_mov_b32_e32 v69, v76
	v_mov_b32_e32 v75, v77
	v_pk_fma_f32 v[70:71], v[70:71], v[112:113], v[98:99]
	v_pk_fma_f32 v[66:67], v[66:67], v[90:91], v[82:83]
	v_pk_add_f32 v[68:69], v[68:69], v[74:75]
.LBB0_727:
	v_add_u32_e32 v76, 0xb0, v155
	v_mov_b32_e32 v74, v132
	v_mov_b32_e32 v75, v132
	v_pk_mul_f32 v[70:71], v[132:133], v[70:71]
	s_or_b32 s2, s30, 0x80
	v_pk_mul_f32 v[72:73], v[74:75], v[72:73]
	v_pk_mul_f32 v[74:75], v[74:75], v[68:69]
	v_pk_mul_f32 v[68:69], v[132:133], v[66:67]
	v_cvt_pk_bf16_f32 v66, v70, v71
	v_mad_i64_i32 v[70:71], s[10:11], v76, s52, 0
	s_cmp_lt_i32 s2, s81
	s_cselect_b64 s[10:11], -1, 0
	s_and_b64 s[34:35], s[10:11], s[34:35]
	v_cvt_pk_bf16_f32 v67, v72, v73
	v_cvt_pk_bf16_f32 v68, v68, v69
	v_cvt_pk_bf16_f32 v69, v74, v75
	v_lshl_add_u64 v[70:71], v[70:71], 1, s[18:19]
	v_cndmask_b32_e64 v74, 0, 1, s[34:35]
	v_lshl_add_u64 v[72:73], v[130:131], 1, v[70:71]
	v_cmp_ne_u32_e64 s[10:11], 1, v74
	s_andn2_b64 vcc, exec, s[34:35]
	global_store_dwordx4 v[72:73], v[66:69], off sc0 sc1
	s_cbranch_vccnz .LBB0_729
	s_nop 0
	v_and_b32_e32 v67, 64, v249
	v_xor_b32_e32 v66, 32, v249
	v_add_u32_e32 v67, 64, v67
	v_cmp_lt_i32_e32 vcc, v66, v67
	s_nop 1
	v_cndmask_b32_e32 v66, v249, v66, vcc
	v_lshlrev_b32_e32 v66, 2, v66
	ds_bpermute_b32 v76, v66, v62
	ds_bpermute_b32 v98, v66, v58
	ds_bpermute_b32 v77, v66, v63
	ds_bpermute_b32 v99, v66, v59
	ds_bpermute_b32 v81, v66, v64
	ds_bpermute_b32 v89, v66, v60
	ds_bpermute_b32 v97, v66, v65
	ds_bpermute_b32 v105, v66, v61
	v_mov_b32_e32 v66, s13
	v_cndmask_b32_e64 v66, v148, v66, s[6:7]
	v_lshl_or_b32 v90, v66, 7, v154
	global_load_dwordx4 v[66:69], v90, s[14:15] offset:48
	global_load_dwordx4 v[72:75], v90, s[14:15] offset:32
	global_load_dwordx4 v[82:85], v90, s[14:15] offset:16
	s_nop 0
	global_load_dwordx4 v[90:93], v90, s[14:15]
	s_waitcnt lgkmcnt(0)
	v_pk_mul_f32 v[76:77], v[142:143], v[76:77]
	v_mul_f32_e32 v81, v142, v81
	s_waitcnt vmcnt(0)
	v_mul_f32_e32 v60, v60, v66
	v_mul_f32_e32 v66, v142, v89
	v_mul_f32_e32 v64, v64, v82
	v_mov_b32_e32 v100, v90
	v_mov_b32_e32 v101, v92
	v_mov_b32_e32 v92, v91
	v_mul_f32_e32 v91, v142, v97
	v_mov_b32_e32 v90, v65
	v_pk_mul_f32 v[84:85], v[90:91], v[84:85]
	v_pk_mul_f32 v[76:77], v[76:77], v[92:93]
	v_mul_f32_e32 v82, v81, v83
	v_mov_b32_e32 v65, v84
	v_mov_b32_e32 v83, v85
	v_pk_fma_f32 v[62:63], v[62:63], v[100:101], v[76:77]
	v_pk_add_f32 v[64:65], v[64:65], v[82:83]
	v_mov_b32_e32 v77, v74
	v_pk_mul_f32 v[82:83], v[142:143], v[98:99]
	v_mov_b32_e32 v74, v73
	v_mov_b32_e32 v76, v72
	v_pk_mul_f32 v[72:73], v[82:83], v[74:75]
	v_mul_f32_e32 v75, v142, v105
	v_mov_b32_e32 v74, v61
	v_pk_mul_f32 v[68:69], v[74:75], v[68:69]
	v_mul_f32_e32 v66, v66, v67
	v_mov_b32_e32 v61, v68
	v_mov_b32_e32 v67, v69
	v_pk_fma_f32 v[58:59], v[58:59], v[76:77], v[72:73]
	v_pk_add_f32 v[60:61], v[60:61], v[66:67]
.LBB0_729:
	s_cmpk_lt_i32 s2, 0x400
	s_cselect_b64 vcc, -1, 0
	v_cndmask_b32_e32 v66, 1.0, v251, vcc
	v_pk_mul_f32 v[62:63], v[66:67], v[62:63] op_sel_hi:[0,1]
	s_ashr_i32 s31, s30, 31
	v_pk_mul_f32 v[64:65], v[66:67], v[64:65] op_sel_hi:[0,1]
	v_pk_mul_f32 v[68:69], v[66:67], v[60:61] op_sel_hi:[0,1]
	v_pk_mul_f32 v[60:61], v[66:67], v[58:59] op_sel_hi:[0,1]
	v_cvt_pk_bf16_f32 v58, v62, v63
	v_lshl_add_u64 v[62:63], s[30:31], 0, v[140:141]
	v_cvt_pk_bf16_f32 v59, v64, v65
	v_lshl_add_u64 v[64:65], v[62:63], 1, v[126:127]
	s_and_b64 vcc, exec, s[10:11]
	v_cvt_pk_bf16_f32 v60, v60, v61
	v_cvt_pk_bf16_f32 v61, v68, v69
	global_store_dwordx4 v[64:65], v[58:61], off offset:256 sc0 sc1
	s_cbranch_vccnz .LBB0_731
	s_nop 0
	v_and_b32_e32 v59, 64, v249
	v_xor_b32_e32 v58, 32, v249
	v_add_u32_e32 v59, 64, v59
	v_cmp_lt_i32_e32 vcc, v58, v59
	s_nop 1
	v_cndmask_b32_e32 v58, v249, v58, vcc
	v_lshlrev_b32_e32 v58, 2, v58
	ds_bpermute_b32 v64, v58, v54
	ds_bpermute_b32 v68, v58, v50
	ds_bpermute_b32 v65, v58, v55
	ds_bpermute_b32 v69, v58, v51
	ds_bpermute_b32 v67, v58, v56
	ds_bpermute_b32 v81, v58, v52
	ds_bpermute_b32 v89, v58, v57
	ds_bpermute_b32 v97, v58, v53
	v_mov_b32_e32 v58, s13
	v_cndmask_b32_e64 v58, v150, v58, s[6:7]
	v_lshl_or_b32 v76, v58, 7, v154
	global_load_dwordx4 v[58:61], v76, s[14:15] offset:48
	global_load_dwordx4 v[72:75], v76, s[14:15] offset:32
	global_load_dwordx4 v[82:85], v76, s[14:15] offset:16
	global_load_dwordx4 v[90:93], v76, s[14:15]
	s_waitcnt lgkmcnt(0)
	v_pk_mul_f32 v[64:65], v[142:143], v[64:65]
	v_mul_f32_e32 v67, v142, v67
	v_pk_mul_f32 v[68:69], v[142:143], v[68:69]
	s_waitcnt vmcnt(0)
	v_mul_f32_e32 v52, v52, v58
	v_mul_f32_e32 v58, v142, v81
	v_mul_f32_e32 v56, v56, v82
	v_mov_b32_e32 v77, v92
	v_mov_b32_e32 v92, v91
	v_mov_b32_e32 v76, v90
	v_pk_mul_f32 v[64:65], v[64:65], v[92:93]
	v_mul_f32_e32 v91, v142, v89
	v_mov_b32_e32 v90, v57
	v_pk_fma_f32 v[54:55], v[54:55], v[76:77], v[64:65]
	v_mov_b32_e32 v64, v72
	v_mov_b32_e32 v65, v74
	v_mov_b32_e32 v74, v73
	v_mul_f32_e32 v73, v142, v97
	v_mov_b32_e32 v72, v53
	v_pk_mul_f32 v[84:85], v[90:91], v[84:85]
	v_pk_mul_f32 v[60:61], v[72:73], v[60:61]
	v_mul_f32_e32 v82, v67, v83
	v_mov_b32_e32 v57, v84
	v_mov_b32_e32 v83, v85
	v_pk_mul_f32 v[68:69], v[68:69], v[74:75]
	v_mul_f32_e32 v58, v58, v59
	v_mov_b32_e32 v53, v60
	v_mov_b32_e32 v59, v61
	v_pk_add_f32 v[56:57], v[56:57], v[82:83]
	v_pk_fma_f32 v[50:51], v[50:51], v[64:65], v[68:69]
	v_pk_add_f32 v[52:53], v[52:53], v[58:59]
.LBB0_731:
	v_mov_b32_e32 v67, v66
	v_mov_b32_e32 v58, v66
	v_mov_b32_e32 v59, v66
	v_pk_mul_f32 v[54:55], v[66:67], v[54:55]
	v_pk_mul_f32 v[60:61], v[58:59], v[52:53]
	v_pk_mul_f32 v[52:53], v[66:67], v[50:51]
	v_cvt_pk_bf16_f32 v50, v54, v55
	v_lshl_add_u64 v[54:55], v[62:63], 1, v[118:119]
	s_and_b64 vcc, exec, s[10:11]
	v_pk_mul_f32 v[56:57], v[58:59], v[56:57]
	s_nop 0
	v_cvt_pk_bf16_f32 v51, v56, v57
	v_cvt_pk_bf16_f32 v52, v52, v53
	v_cvt_pk_bf16_f32 v53, v60, v61
	global_store_dwordx4 v[54:55], v[50:53], off offset:256 sc0 sc1
	s_cbranch_vccnz .LBB0_733
	s_nop 0
	v_and_b32_e32 v51, 64, v249
	v_xor_b32_e32 v50, 32, v249
	v_add_u32_e32 v51, 64, v51
	v_cmp_lt_i32_e32 vcc, v50, v51
	s_nop 1
	v_cndmask_b32_e32 v50, v249, v50, vcc
	v_lshlrev_b32_e32 v50, 2, v50
	ds_bpermute_b32 v60, v50, v46
	ds_bpermute_b32 v64, v50, v42
	ds_bpermute_b32 v61, v50, v47
	ds_bpermute_b32 v65, v50, v43
	ds_bpermute_b32 v76, v50, v48
	ds_bpermute_b32 v81, v50, v44
	ds_bpermute_b32 v77, v50, v49
	ds_bpermute_b32 v89, v50, v45
	v_mov_b32_e32 v50, s13
	v_cndmask_b32_e64 v50, v151, v50, s[6:7]
	v_lshl_or_b32 v68, v50, 7, v154
	global_load_dwordx4 v[50:53], v68, s[14:15] offset:48
	global_load_dwordx4 v[54:57], v68, s[14:15] offset:32
	global_load_dwordx4 v[72:75], v68, s[14:15] offset:16
	global_load_dwordx4 v[82:85], v68, s[14:15]
	s_waitcnt lgkmcnt(0)
	v_pk_mul_f32 v[60:61], v[142:143], v[60:61]
	v_pk_mul_f32 v[64:65], v[142:143], v[64:65]
	v_mul_f32_e32 v77, v142, v77
	s_waitcnt vmcnt(0)
	v_mul_f32_e32 v44, v44, v50
	v_mul_f32_e32 v50, v142, v81
	v_mul_f32_e32 v48, v48, v72
	v_mov_b32_e32 v69, v84
	v_mov_b32_e32 v84, v83
	v_mov_b32_e32 v68, v82
	v_pk_mul_f32 v[60:61], v[60:61], v[84:85]
	v_mul_f32_e32 v72, v142, v76
	v_pk_fma_f32 v[46:47], v[46:47], v[68:69], v[60:61]
	v_mov_b32_e32 v61, v56
	v_mov_b32_e32 v56, v55
	v_mov_b32_e32 v76, v49
	v_mov_b32_e32 v60, v54
	v_pk_mul_f32 v[54:55], v[64:65], v[56:57]
	v_mul_f32_e32 v57, v142, v89
	v_mov_b32_e32 v56, v45
	v_pk_mul_f32 v[74:75], v[76:77], v[74:75]
	v_pk_mul_f32 v[52:53], v[56:57], v[52:53]
	v_mul_f32_e32 v72, v72, v73
	v_mov_b32_e32 v49, v74
	v_mov_b32_e32 v73, v75
	v_mul_f32_e32 v50, v50, v51
	v_mov_b32_e32 v45, v52
	v_mov_b32_e32 v51, v53
	v_pk_add_f32 v[48:49], v[48:49], v[72:73]
	v_pk_fma_f32 v[42:43], v[42:43], v[60:61], v[54:55]
	v_pk_add_f32 v[44:45], v[44:45], v[50:51]
.LBB0_733:
	v_pk_mul_f32 v[46:47], v[66:67], v[46:47]
	v_pk_mul_f32 v[50:51], v[58:59], v[44:45]
	v_pk_mul_f32 v[44:45], v[66:67], v[42:43]
	v_cvt_pk_bf16_f32 v42, v46, v47
	v_lshl_add_u64 v[46:47], v[62:63], 1, v[110:111]
	s_and_b64 vcc, exec, s[10:11]
	v_pk_mul_f32 v[48:49], v[58:59], v[48:49]
	s_nop 0
	v_cvt_pk_bf16_f32 v43, v48, v49
	v_cvt_pk_bf16_f32 v44, v44, v45
	v_cvt_pk_bf16_f32 v45, v50, v51
	global_store_dwordx4 v[46:47], v[42:45], off offset:256 sc0 sc1
	s_cbranch_vccnz .LBB0_735
	s_nop 0
	v_mov_b32_e32 v42, s13
	v_cndmask_b32_e64 v42, v152, v42, s[6:7]
	v_lshl_or_b32 v54, v42, 7, v154
	global_load_dwordx4 v[42:45], v54, s[14:15]
	global_load_dwordx4 v[46:49], v54, s[14:15] offset:16
	global_load_dwordx4 v[50:53], v54, s[14:15] offset:32
	s_nop 0
	global_load_dwordx4 v[54:57], v54, s[14:15] offset:48
	v_and_b32_e32 v61, 64, v249
	v_xor_b32_e32 v59, 32, v249
	v_add_u32_e32 v61, 64, v61
	v_cmp_lt_i32_e32 vcc, v59, v61
	v_mov_b32_e32 v58, v41
	v_mov_b32_e32 v60, v37
	v_cndmask_b32_e32 v59, v249, v59, vcc
	v_lshlrev_b32_e32 v59, 2, v59
	ds_bpermute_b32 v61, v59, v40
	ds_bpermute_b32 v41, v59, v41
	ds_bpermute_b32 v72, v59, v36
	ds_bpermute_b32 v37, v59, v37
	ds_bpermute_b32 v64, v59, v38
	ds_bpermute_b32 v68, v59, v34
	ds_bpermute_b32 v65, v59, v39
	ds_bpermute_b32 v69, v59, v35
	s_waitcnt lgkmcnt(0)
	v_mul_f32_e32 v74, v142, v61
	v_mul_f32_e32 v59, v142, v41
	v_mul_f32_e32 v41, v142, v72
	v_mul_f32_e32 v61, v142, v37
	v_pk_mul_f32 v[64:65], v[142:143], v[64:65]
	v_pk_mul_f32 v[68:69], v[142:143], v[68:69]
	s_waitcnt vmcnt(0)
	v_mov_b32_e32 v72, v42
	v_mov_b32_e32 v73, v44
	v_mov_b32_e32 v44, v43
	v_mul_f32_e32 v40, v40, v46
	v_mul_f32_e32 v42, v74, v47
	v_pk_mul_f32 v[46:47], v[58:59], v[48:49]
	v_mov_b32_e32 v48, v50
	v_mov_b32_e32 v49, v52
	v_mov_b32_e32 v52, v51
	v_mul_f32_e32 v36, v36, v54
	v_mul_f32_e32 v50, v41, v55
	v_pk_mul_f32 v[54:55], v[60:61], v[56:57]
	v_pk_mul_f32 v[44:45], v[64:65], v[44:45]
	v_mov_b32_e32 v41, v46
	v_mov_b32_e32 v43, v47
	v_pk_mul_f32 v[46:47], v[68:69], v[52:53]
	v_mov_b32_e32 v37, v54
	v_mov_b32_e32 v51, v55
	v_pk_fma_f32 v[38:39], v[38:39], v[72:73], v[44:45]
	v_pk_add_f32 v[40:41], v[40:41], v[42:43]
	v_pk_fma_f32 v[34:35], v[34:35], v[48:49], v[46:47]
	v_pk_add_f32 v[36:37], v[36:37], v[50:51]
.LBB0_735:
	s_nop 0
	v_mov_b32_e32 v42, v66
	v_mov_b32_e32 v43, v66
	v_pk_mul_f32 v[38:39], v[66:67], v[38:39]
	v_pk_mul_f32 v[44:45], v[42:43], v[36:37]
	v_pk_mul_f32 v[36:37], v[66:67], v[34:35]
	v_cvt_pk_bf16_f32 v34, v38, v39
	v_lshl_add_u64 v[38:39], v[62:63], 1, v[102:103]
	s_and_b64 vcc, exec, s[10:11]
	v_pk_mul_f32 v[40:41], v[42:43], v[40:41]
	s_nop 0
	v_cvt_pk_bf16_f32 v35, v40, v41
	v_cvt_pk_bf16_f32 v36, v36, v37
	v_cvt_pk_bf16_f32 v37, v44, v45
	global_store_dwordx4 v[38:39], v[34:37], off offset:256 sc0 sc1
	s_cbranch_vccnz .LBB0_737
	s_nop 0
	v_and_b32_e32 v35, 64, v249
	v_xor_b32_e32 v34, 32, v249
	v_add_u32_e32 v35, 64, v35
	v_cmp_lt_i32_e32 vcc, v34, v35
	s_nop 1
	v_cndmask_b32_e32 v34, v249, v34, vcc
	v_lshlrev_b32_e32 v34, 2, v34
	ds_bpermute_b32 v52, v34, v30
	ds_bpermute_b32 v54, v34, v26
	ds_bpermute_b32 v53, v34, v31
	ds_bpermute_b32 v55, v34, v27
	ds_bpermute_b32 v58, v34, v32
	ds_bpermute_b32 v59, v34, v28
	ds_bpermute_b32 v60, v34, v33
	ds_bpermute_b32 v61, v34, v29
	global_load_dwordx4 v[34:37], v104, s[14:15] offset:48
	global_load_dwordx4 v[38:41], v104, s[14:15] offset:32
	global_load_dwordx4 v[44:47], v104, s[14:15] offset:16
	global_load_dwordx4 v[48:51], v104, s[14:15]
	s_waitcnt lgkmcnt(0)
	v_pk_mul_f32 v[52:53], v[142:143], v[52:53]
	s_waitcnt vmcnt(0)
	v_mul_f32_e32 v28, v28, v34
	v_mul_f32_e32 v34, v142, v59
	v_mul_f32_e32 v32, v32, v44
	v_mov_b32_e32 v57, v50
	v_mov_b32_e32 v50, v49
	v_mov_b32_e32 v56, v48
	v_pk_mul_f32 v[48:49], v[52:53], v[50:51]
	v_mul_f32_e32 v51, v142, v60
	v_mov_b32_e32 v50, v33
	v_mul_f32_e32 v44, v142, v58
	v_pk_mul_f32 v[46:47], v[50:51], v[46:47]
	v_mul_f32_e32 v44, v44, v45
	v_mov_b32_e32 v33, v46
	v_mov_b32_e32 v45, v47
	v_pk_add_f32 v[32:33], v[32:33], v[44:45]
	v_mov_b32_e32 v45, v40
	v_pk_mul_f32 v[46:47], v[142:143], v[54:55]
	v_mov_b32_e32 v40, v39
	v_mov_b32_e32 v44, v38
	v_pk_mul_f32 v[38:39], v[46:47], v[40:41]
	v_mul_f32_e32 v41, v142, v61
	v_mov_b32_e32 v40, v29
	v_pk_mul_f32 v[36:37], v[40:41], v[36:37]
	v_mul_f32_e32 v34, v34, v35
	v_mov_b32_e32 v29, v36
	v_mov_b32_e32 v35, v37
	v_pk_fma_f32 v[30:31], v[30:31], v[56:57], v[48:49]
	v_pk_fma_f32 v[26:27], v[26:27], v[44:45], v[38:39]
	v_pk_add_f32 v[28:29], v[28:29], v[34:35]
.LBB0_737:
	v_pk_mul_f32 v[30:31], v[66:67], v[30:31]
	v_pk_mul_f32 v[34:35], v[42:43], v[28:29]
	v_pk_mul_f32 v[28:29], v[66:67], v[26:27]
	v_cvt_pk_bf16_f32 v26, v30, v31
	v_lshl_add_u64 v[30:31], v[62:63], 1, v[94:95]
	s_and_b64 vcc, exec, s[10:11]
	v_pk_mul_f32 v[32:33], v[42:43], v[32:33]
	s_nop 0
	v_cvt_pk_bf16_f32 v27, v32, v33
	v_cvt_pk_bf16_f32 v28, v28, v29
	v_cvt_pk_bf16_f32 v29, v34, v35
	global_store_dwordx4 v[30:31], v[26:29], off offset:256 sc0 sc1
	s_cbranch_vccnz .LBB0_739
	s_nop 0
	v_and_b32_e32 v27, 64, v249
	v_xor_b32_e32 v26, 32, v249
	v_add_u32_e32 v27, 64, v27
	v_cmp_lt_i32_e32 vcc, v26, v27
	s_nop 1
	v_cndmask_b32_e32 v26, v249, v26, vcc
	v_lshlrev_b32_e32 v26, 2, v26
	ds_bpermute_b32 v42, v26, v22
	ds_bpermute_b32 v44, v26, v18
	ds_bpermute_b32 v43, v26, v23
	ds_bpermute_b32 v45, v26, v19
	ds_bpermute_b32 v48, v26, v24
	ds_bpermute_b32 v49, v26, v20
	ds_bpermute_b32 v50, v26, v25
	ds_bpermute_b32 v51, v26, v21
	global_load_dwordx4 v[26:29], v96, s[14:15] offset:48
	global_load_dwordx4 v[30:33], v96, s[14:15] offset:32
	global_load_dwordx4 v[34:37], v96, s[14:15] offset:16
	global_load_dwordx4 v[38:41], v96, s[14:15]
	s_waitcnt lgkmcnt(0)
	v_pk_mul_f32 v[42:43], v[142:143], v[42:43]
	s_waitcnt vmcnt(0)
	v_mul_f32_e32 v20, v20, v26
	v_mul_f32_e32 v26, v142, v49
	v_mul_f32_e32 v24, v24, v34
	v_mov_b32_e32 v47, v40
	v_mov_b32_e32 v40, v39
	v_mov_b32_e32 v46, v38
	v_pk_mul_f32 v[38:39], v[42:43], v[40:41]
	v_mul_f32_e32 v41, v142, v50
	v_mov_b32_e32 v40, v25
	v_mul_f32_e32 v34, v142, v48
	v_pk_mul_f32 v[36:37], v[40:41], v[36:37]
	v_mul_f32_e32 v34, v34, v35
	v_mov_b32_e32 v25, v36
	v_mov_b32_e32 v35, v37
	v_pk_add_f32 v[24:25], v[24:25], v[34:35]
	v_mov_b32_e32 v35, v32
	v_pk_mul_f32 v[36:37], v[142:143], v[44:45]
	v_mov_b32_e32 v32, v31
	v_mov_b32_e32 v34, v30
	v_pk_mul_f32 v[30:31], v[36:37], v[32:33]
	v_mul_f32_e32 v33, v142, v51
	v_mov_b32_e32 v32, v21
	v_pk_mul_f32 v[28:29], v[32:33], v[28:29]
	v_mul_f32_e32 v26, v26, v27
	v_mov_b32_e32 v21, v28
	v_mov_b32_e32 v27, v29
	v_pk_fma_f32 v[22:23], v[22:23], v[46:47], v[38:39]
	v_pk_fma_f32 v[18:19], v[18:19], v[34:35], v[30:31]
	v_pk_add_f32 v[20:21], v[20:21], v[26:27]
.LBB0_739:
	s_nop 0
	v_mov_b32_e32 v26, v66
	v_mov_b32_e32 v27, v66
	v_pk_mul_f32 v[22:23], v[66:67], v[22:23]
	v_pk_mul_f32 v[28:29], v[26:27], v[20:21]
	v_pk_mul_f32 v[20:21], v[66:67], v[18:19]
	v_cvt_pk_bf16_f32 v18, v22, v23
	v_lshl_add_u64 v[22:23], v[62:63], 1, v[86:87]
	s_and_b64 vcc, exec, s[10:11]
	v_pk_mul_f32 v[24:25], v[26:27], v[24:25]
	s_nop 0
	v_cvt_pk_bf16_f32 v19, v24, v25
	v_cvt_pk_bf16_f32 v20, v20, v21
	v_cvt_pk_bf16_f32 v21, v28, v29
	global_store_dwordx4 v[22:23], v[18:21], off offset:256 sc0 sc1
	s_cbranch_vccnz .LBB0_741
	s_nop 0
	v_and_b32_e32 v19, 64, v249
	v_xor_b32_e32 v18, 32, v249
	v_add_u32_e32 v19, 64, v19
	v_cmp_lt_i32_e32 vcc, v18, v19
	s_nop 1
	v_cndmask_b32_e32 v18, v249, v18, vcc
	v_lshlrev_b32_e32 v18, 2, v18
	ds_bpermute_b32 v36, v18, v14
	ds_bpermute_b32 v38, v18, v10
	ds_bpermute_b32 v37, v18, v15
	ds_bpermute_b32 v39, v18, v11
	ds_bpermute_b32 v42, v18, v16
	ds_bpermute_b32 v43, v18, v12
	ds_bpermute_b32 v44, v18, v17
	ds_bpermute_b32 v45, v18, v13
	global_load_dwordx4 v[18:21], v88, s[14:15] offset:48
	global_load_dwordx4 v[22:25], v88, s[14:15] offset:32
	global_load_dwordx4 v[28:31], v88, s[14:15] offset:16
	global_load_dwordx4 v[32:35], v88, s[14:15]
	s_waitcnt lgkmcnt(0)
	v_pk_mul_f32 v[36:37], v[142:143], v[36:37]
	s_waitcnt vmcnt(0)
	v_mul_f32_e32 v12, v12, v18
	v_mul_f32_e32 v18, v142, v43
	v_mul_f32_e32 v16, v16, v28
	v_mov_b32_e32 v41, v34
	v_mov_b32_e32 v34, v33
	v_mov_b32_e32 v40, v32
	v_pk_mul_f32 v[32:33], v[36:37], v[34:35]
	v_mul_f32_e32 v35, v142, v44
	v_mov_b32_e32 v34, v17
	v_mul_f32_e32 v28, v142, v42
	v_pk_mul_f32 v[30:31], v[34:35], v[30:31]
	v_mul_f32_e32 v28, v28, v29
	v_mov_b32_e32 v17, v30
	v_mov_b32_e32 v29, v31
	v_pk_add_f32 v[16:17], v[16:17], v[28:29]
	v_mov_b32_e32 v29, v24
	v_pk_mul_f32 v[30:31], v[142:143], v[38:39]
	v_mov_b32_e32 v24, v23
	v_mov_b32_e32 v28, v22
	v_pk_mul_f32 v[22:23], v[30:31], v[24:25]
	v_mul_f32_e32 v25, v142, v45
	v_mov_b32_e32 v24, v13
	v_pk_mul_f32 v[20:21], v[24:25], v[20:21]
	v_mul_f32_e32 v18, v18, v19
	v_mov_b32_e32 v13, v20
	v_mov_b32_e32 v19, v21
	v_pk_fma_f32 v[14:15], v[14:15], v[40:41], v[32:33]
	v_pk_fma_f32 v[10:11], v[10:11], v[28:29], v[22:23]
	v_pk_add_f32 v[12:13], v[12:13], v[18:19]
.LBB0_741:
	v_pk_mul_f32 v[14:15], v[66:67], v[14:15]
	v_pk_mul_f32 v[18:19], v[26:27], v[12:13]
	v_pk_mul_f32 v[12:13], v[66:67], v[10:11]
	v_cvt_pk_bf16_f32 v10, v14, v15
	v_lshl_add_u64 v[14:15], v[62:63], 1, v[78:79]
	s_and_b64 vcc, exec, s[10:11]
	v_pk_mul_f32 v[16:17], v[26:27], v[16:17]
	s_nop 0
	v_cvt_pk_bf16_f32 v11, v16, v17
	v_cvt_pk_bf16_f32 v12, v12, v13
	v_cvt_pk_bf16_f32 v13, v18, v19
	global_store_dwordx4 v[14:15], v[10:13], off offset:256 sc0 sc1
	s_cbranch_vccnz .LBB0_743
	s_nop 0
	v_and_b32_e32 v11, 64, v249
	v_xor_b32_e32 v10, 32, v249
	v_add_u32_e32 v11, 64, v11
	v_cmp_lt_i32_e32 vcc, v10, v11
	s_nop 1
	v_cndmask_b32_e32 v10, v249, v10, vcc
	v_lshlrev_b32_e32 v10, 2, v10
	ds_bpermute_b32 v26, v10, v6
	ds_bpermute_b32 v28, v10, v2
	ds_bpermute_b32 v27, v10, v7
	ds_bpermute_b32 v29, v10, v3
	ds_bpermute_b32 v32, v10, v8
	ds_bpermute_b32 v33, v10, v4
	ds_bpermute_b32 v34, v10, v9
	ds_bpermute_b32 v35, v10, v5
	global_load_dwordx4 v[10:13], v80, s[14:15] offset:48
	global_load_dwordx4 v[14:17], v80, s[14:15] offset:32
	global_load_dwordx4 v[18:21], v80, s[14:15] offset:16
	global_load_dwordx4 v[22:25], v80, s[14:15]
	s_waitcnt lgkmcnt(0)
	v_pk_mul_f32 v[26:27], v[142:143], v[26:27]
	s_waitcnt vmcnt(0)
	v_mul_f32_e32 v4, v4, v10
	v_mul_f32_e32 v10, v142, v33
	v_mul_f32_e32 v8, v8, v18
	v_mov_b32_e32 v31, v24
	v_mov_b32_e32 v24, v23
	v_mov_b32_e32 v30, v22
	v_pk_mul_f32 v[22:23], v[26:27], v[24:25]
	v_mul_f32_e32 v25, v142, v34
	v_mov_b32_e32 v24, v9
	v_mul_f32_e32 v18, v142, v32
	v_pk_mul_f32 v[20:21], v[24:25], v[20:21]
	v_mul_f32_e32 v18, v18, v19
	v_mov_b32_e32 v9, v20
	v_mov_b32_e32 v19, v21
	v_pk_add_f32 v[8:9], v[8:9], v[18:19]
	v_mov_b32_e32 v19, v16
	v_pk_mul_f32 v[20:21], v[142:143], v[28:29]
	v_mov_b32_e32 v16, v15
	v_mov_b32_e32 v18, v14
	v_pk_mul_f32 v[14:15], v[20:21], v[16:17]
	v_mul_f32_e32 v17, v142, v35
	v_mov_b32_e32 v16, v5
	v_pk_mul_f32 v[12:13], v[16:17], v[12:13]
	v_mul_f32_e32 v10, v10, v11
	v_mov_b32_e32 v5, v12
	v_mov_b32_e32 v11, v13
	v_pk_fma_f32 v[6:7], v[6:7], v[30:31], v[22:23]
	v_pk_fma_f32 v[2:3], v[2:3], v[18:19], v[14:15]
	v_pk_add_f32 v[4:5], v[4:5], v[10:11]
.LBB0_743:
	s_nop 0
	v_mov_b32_e32 v10, v66
	v_mov_b32_e32 v11, v66
	v_pk_mul_f32 v[6:7], v[66:67], v[6:7]
	v_pk_mul_f32 v[8:9], v[10:11], v[8:9]
	v_pk_mul_f32 v[10:11], v[10:11], v[4:5]
	v_pk_mul_f32 v[4:5], v[66:67], v[2:3]
	v_cvt_pk_bf16_f32 v2, v6, v7
	v_lshl_add_u64 v[6:7], v[62:63], 1, v[70:71]
	s_andn2_b64 vcc, exec, s[8:9]
	s_mov_b64 s[8:9], -1
	v_cvt_pk_bf16_f32 v3, v8, v9
	v_cvt_pk_bf16_f32 v4, v4, v5
	v_cvt_pk_bf16_f32 v5, v10, v11
	global_store_dwordx4 v[6:7], v[2:5], off offset:256 sc0 sc1
	s_cbranch_vccnz .LBB0_704
	s_andn2_b64 vcc, exec, s[16:17]
	s_cbranch_vccnz .LBB0_703
	s_barrier
	s_branch .LBB0_703

.LBB0_1167:
	s_and_b64 vcc, exec, s[6:7]
	s_movk_i32 s65, 0xff5d
	s_movk_i32 s64, 0xff7c
	s_cbranch_vccnz .LBB0_1171
	s_lshr_b32 s2, s86, 5
	s_and_b32 s2, s2, 0x7800000
	s_add_u32 s2, s15, s2
	v_lshl_or_b32 v156, s16, 8, v154
	s_addc_u32 s16, s52, 0
	s_lshl_b32 s6, s14, 8
	s_ashr_i32 s7, s6, 31
	s_lshl_b64 s[6:7], s[6:7], 12
	s_add_u32 s6, s2, s6
	s_addc_u32 s7, s16, s7
	v_ashrrev_i32_e32 v157, 31, v156
	v_lshl_add_u64 v[156:157], v[156:157], 2, s[6:7]
	s_brev_b32 s6, 63
	s_mov_b32 s7, -1
	v_lshl_add_u64 v[156:157], v[156:157], 0, s[6:7]
	v_lshl_add_u64 v[158:159], v[156:157], 0, v[132:133]
	global_store_dwordx4 v[158:159], v[122:125], off sc0 sc1
	global_store_dwordx4 v[158:159], v[102:105], off offset:64 sc0 sc1
	global_store_dwordx4 v[158:159], v[70:73], off offset:512 sc0 sc1
	global_store_dwordx4 v[158:159], v[126:129], off offset:576 sc0 sc1
	s_andn2_b64 vcc, exec, s[20:21]
	v_lshl_add_u64 v[70:71], v[156:157], 0, v[134:135]
	global_store_dwordx4 v[70:71], v[118:121], off sc0 sc1
	global_store_dwordx4 v[70:71], v[94:97], off offset:64 sc0 sc1
	global_store_dwordx4 v[70:71], v[66:69], off offset:512 sc0 sc1
	global_store_dwordx4 v[70:71], v[42:45], off offset:576 sc0 sc1
	s_nop 1
	v_lshl_add_u64 v[42:43], v[156:157], 0, v[136:137]
	global_store_dwordx4 v[42:43], v[114:117], off sc0 sc1
	global_store_dwordx4 v[42:43], v[90:93], off offset:64 sc0 sc1
	global_store_dwordx4 v[42:43], v[50:53], off offset:512 sc0 sc1
	global_store_dwordx4 v[42:43], v[30:33], off offset:576 sc0 sc1
	s_nop 1
	v_lshl_add_u64 v[30:31], v[156:157], 0, v[138:139]
	global_store_dwordx4 v[30:31], v[110:113], off sc0 sc1
	global_store_dwordx4 v[30:31], v[82:85], off offset:64 sc0 sc1
	global_store_dwordx4 v[30:31], v[46:49], off offset:512 sc0 sc1
	global_store_dwordx4 v[30:31], v[26:29], off offset:576 sc0 sc1
	s_nop 1
	v_lshl_add_u64 v[26:27], v[156:157], 0, v[140:141]
	global_store_dwordx4 v[26:27], v[106:109], off sc0 sc1
	global_store_dwordx4 v[26:27], v[74:77], off offset:64 sc0 sc1
	global_store_dwordx4 v[26:27], v[38:41], off offset:512 sc0 sc1
	global_store_dwordx4 v[26:27], v[22:25], off offset:576 sc0 sc1
	s_nop 1
	v_lshl_add_u64 v[22:23], v[156:157], 0, v[142:143]
	global_store_dwordx4 v[22:23], v[98:101], off sc0 sc1
	global_store_dwordx4 v[22:23], v[62:65], off offset:64 sc0 sc1
	global_store_dwordx4 v[22:23], v[34:37], off offset:512 sc0 sc1
	global_store_dwordx4 v[22:23], v[14:17], off offset:576 sc0 sc1
	s_nop 1
	v_lshl_add_u64 v[14:15], v[156:157], 0, v[144:145]
	global_store_dwordx4 v[14:15], v[86:89], off sc0 sc1
	global_store_dwordx4 v[14:15], v[58:61], off offset:64 sc0 sc1
	global_store_dwordx4 v[14:15], v[18:21], off offset:512 sc0 sc1
	global_store_dwordx4 v[14:15], v[6:9], off offset:576 sc0 sc1
	s_nop 1
	v_lshl_add_u64 v[6:7], v[156:157], 0, v[146:147]
	global_store_dwordx4 v[6:7], v[78:81], off sc0 sc1
	global_store_dwordx4 v[6:7], v[54:57], off offset:64 sc0 sc1
	global_store_dwordx4 v[6:7], v[10:13], off offset:512 sc0 sc1
	global_store_dwordx4 v[6:7], v[2:5], off offset:576 sc0 sc1
	s_cbranch_vccnz .LBB0_1170
	s_barrier
